# accumulator zeroing with v_mov_b64 (64 instead of 128 moves per unit) on top of C1 rewrite and GLA changes
# speedup vs baseline: 1.0123x; 1.0059x over previous
; template <class Epi, class Sched, bool ALIGN_EPI = false, bool SP2 = false>
; __device__ __forceinline__ void gemm_phase(PG8_LAS unsigned char* lds, const Gemm g, const Sched& S, const Epi& E, const int wave_s) {
;     ...
;         const bool has_next = S.next(ui + 1, nxt);
;         const char* nA = has_next ? (const char*)g.A + (size_t)nxt.pm * tstep : cA; const char* nB = has_next ? (const char*)g.Bt + (size_t)nxt.pn * tstep : cB;
;         for (int t = 0; t < nt; t += 2) {
;             const bool last = (t == nt - 2);
;             const char* a1 = cA + (size_t)(t + 1) * kstep;
;             const char* a2 = last ? nA : cA + (size_t)(t + 2) * kstep; const char* b2 = last ? nB : cB + (size_t)(t + 2) * kstep;
;             const char* a3 = a2 + kstep; const char* b3 = b2 + kstep;
;     ...
; #pragma unroll
;         for (int a = 0; a < 2; ++a)
; #pragma unroll
;             for (int b = 0; b < 2; ++b)
; #pragma unroll
;                 for (int m = 0; m < 4; ++m)
; #pragma unroll
;                     for (int n = 0; n < 2; ++n) acc[a][b][m][n] = (f32x4){0.f, 0.f, 0.f, 0.f};
;         cur = nxt; cA = nA; cB = nB; ++ui;
.LBB0_181:
	s_ashr_i32 s19, s18, 31
	v_cmp_lt_i64_e32 vcc, s[20:21], v[140:141]
	s_lshl_b64 s[20:21], s[18:19], 19
	s_add_u32 s20, s34, s20
	s_addc_u32 s21, s35, s21
	s_and_b64 s[22:23], vcc, exec
	s_cselect_b32 s19, s21, s29
	s_cselect_b32 s25, s20, s28
	s_ashr_i32 s17, s16, 31
	s_lshl_b64 s[22:23], s[16:17], 19
	s_add_u32 s22, s36, s22
	s_addc_u32 s23, s37, s23
	s_and_b64 s[30:31], vcc, exec
	s_cselect_b32 s17, s23, s27
	s_cselect_b32 s53, s22, s26
	s_add_u32 s54, s26, 0x100
	s_addc_u32 s55, s27, 0
	s_add_u32 s26, s28, 0x40080
	v_mov_b32_e32 v0, 0
	s_addc_u32 s27, s29, 0
	s_mov_b32 s56, -2
	v_mov_b64_e32 v[2:3], 0
	v_mov_b64_e32 v[4:5], 0
	v_mov_b64_e32 v[6:7], 0
	v_mov_b64_e32 v[8:9], 0
	v_mov_b64_e32 v[10:11], 0
	v_mov_b64_e32 v[12:13], 0
	v_mov_b64_e32 v[14:15], 0
	v_mov_b64_e32 v[16:17], 0
	v_mov_b64_e32 v[18:19], 0
	v_mov_b64_e32 v[20:21], 0
	v_mov_b64_e32 v[22:23], 0
	v_mov_b64_e32 v[24:25], 0
	v_mov_b64_e32 v[26:27], 0
	v_mov_b64_e32 v[28:29], 0
	v_mov_b64_e32 v[30:31], 0
	v_mov_b64_e32 v[32:33], 0
	v_mov_b64_e32 v[34:35], 0
	v_mov_b64_e32 v[36:37], 0
	v_mov_b64_e32 v[38:39], 0
	v_mov_b64_e32 v[40:41], 0
	v_mov_b64_e32 v[42:43], 0
	v_mov_b64_e32 v[44:45], 0
	v_mov_b64_e32 v[46:47], 0
	v_mov_b64_e32 v[48:49], 0
	v_mov_b64_e32 v[50:51], 0
	v_mov_b64_e32 v[52:53], 0
	v_mov_b64_e32 v[54:55], 0
	v_mov_b64_e32 v[56:57], 0
	v_mov_b64_e32 v[58:59], 0
	v_mov_b64_e32 v[60:61], 0
	v_mov_b64_e32 v[62:63], 0
	v_mov_b64_e32 v[64:65], 0
	v_mov_b64_e32 v[66:67], 0
	v_mov_b64_e32 v[68:69], 0
	v_mov_b64_e32 v[70:71], 0
	v_mov_b64_e32 v[72:73], 0
	v_mov_b64_e32 v[74:75], 0
	v_mov_b64_e32 v[76:77], 0
	v_mov_b64_e32 v[78:79], 0
	v_mov_b64_e32 v[80:81], 0
	v_mov_b64_e32 v[82:83], 0
	v_mov_b64_e32 v[84:85], 0
	v_mov_b64_e32 v[86:87], 0
	v_mov_b64_e32 v[88:89], 0
	v_mov_b64_e32 v[90:91], 0
	v_mov_b64_e32 v[92:93], 0
	v_mov_b64_e32 v[94:95], 0
	v_mov_b64_e32 v[96:97], 0
	v_mov_b64_e32 v[98:99], 0
	v_mov_b64_e32 v[100:101], 0
	v_mov_b64_e32 v[102:103], 0
	v_mov_b64_e32 v[104:105], 0
	v_mov_b64_e32 v[106:107], 0
	v_mov_b64_e32 v[108:109], 0
	v_mov_b64_e32 v[110:111], 0
	v_mov_b64_e32 v[112:113], 0
	v_mov_b64_e32 v[114:115], 0
	v_mov_b64_e32 v[116:117], 0
	v_mov_b64_e32 v[118:119], 0
	v_mov_b64_e32 v[120:121], 0
	v_mov_b64_e32 v[122:123], 0
	v_mov_b64_e32 v[124:125], 0
	v_mov_b64_e32 v[126:127], 0
	v_mov_b32_e32 v1, v0

; template <class Epi, class Sched, bool ALIGN_EPI = false, bool SP2 = false>
; __device__ __forceinline__ void gemm_phase(PG8_LAS unsigned char* lds, const Gemm g, const Sched& S, const Epi& E, const int wave_s) {
;     ...
;         const bool has_next = S.next(ui + 1, nxt);
;         const char* nA = has_next ? (const char*)g.A + (size_t)nxt.pm * tstep : cA; const char* nB = has_next ? (const char*)g.Bt + (size_t)nxt.pn * tstep : cB;
;         for (int t = 0; t < nt; t += 2) {
;             const bool last = (t == nt - 2);
;             const char* a1 = cA + (size_t)(t + 1) * kstep;
;             const char* a2 = last ? nA : cA + (size_t)(t + 2) * kstep; const char* b2 = last ? nB : cB + (size_t)(t + 2) * kstep;
;             const char* a3 = a2 + kstep; const char* b3 = b2 + kstep;
;     ...
; #pragma unroll
;         for (int a = 0; a < 2; ++a)
; #pragma unroll
;             for (int b = 0; b < 2; ++b)
; #pragma unroll
;                 for (int m = 0; m < 4; ++m)
; #pragma unroll
;                     for (int n = 0; n < 2; ++n) acc[a][b][m][n] = (f32x4){0.f, 0.f, 0.f, 0.f};
;         cur = nxt; cA = nA; cB = nB; ++ui;
.LBB0_482:
	s_ashr_i32 s11, s10, 31
	v_cmp_lt_i64_e32 vcc, s[12:13], v[148:149]
	s_lshl_b64 s[12:13], s[10:11], 18
	s_add_u32 s12, s24, s12
	s_addc_u32 s13, s25, s13
	s_and_b64 s[14:15], vcc, exec
	s_cselect_b32 s11, s13, s21
	s_cselect_b32 s44, s12, s20
	s_ashr_i32 s9, s8, 31
	s_lshl_b64 s[14:15], s[8:9], 18
	s_add_u32 s14, s26, s14
	s_addc_u32 s15, s27, s15
	s_and_b64 s[22:23], vcc, exec
	s_cselect_b32 s9, s15, s19
	s_cselect_b32 s45, s14, s18
	s_add_u32 s46, s18, 0x100
	s_addc_u32 s47, s19, 0
	s_add_u32 s18, s20, 0x20080
	v_mov_b32_e32 v0, 0
	s_addc_u32 s19, s21, 0
	s_mov_b32 s48, -2
	v_mov_b64_e32 v[2:3], 0
	v_mov_b64_e32 v[4:5], 0
	v_mov_b64_e32 v[6:7], 0
	v_mov_b64_e32 v[8:9], 0
	v_mov_b64_e32 v[10:11], 0
	v_mov_b64_e32 v[12:13], 0
	v_mov_b64_e32 v[14:15], 0
	v_mov_b64_e32 v[16:17], 0
	v_mov_b64_e32 v[18:19], 0
	v_mov_b64_e32 v[20:21], 0
	v_mov_b64_e32 v[22:23], 0
	v_mov_b64_e32 v[24:25], 0
	v_mov_b64_e32 v[26:27], 0
	v_mov_b64_e32 v[28:29], 0
	v_mov_b64_e32 v[30:31], 0
	v_mov_b64_e32 v[32:33], 0
	v_mov_b64_e32 v[34:35], 0
	v_mov_b64_e32 v[36:37], 0
	v_mov_b64_e32 v[38:39], 0
	v_mov_b64_e32 v[40:41], 0
	v_mov_b64_e32 v[42:43], 0
	v_mov_b64_e32 v[44:45], 0
	v_mov_b64_e32 v[46:47], 0
	v_mov_b64_e32 v[48:49], 0
	v_mov_b64_e32 v[50:51], 0
	v_mov_b64_e32 v[52:53], 0
	v_mov_b64_e32 v[54:55], 0
	v_mov_b64_e32 v[56:57], 0
	v_mov_b64_e32 v[58:59], 0
	v_mov_b64_e32 v[60:61], 0
	v_mov_b64_e32 v[62:63], 0
	v_mov_b64_e32 v[64:65], 0
	v_mov_b64_e32 v[66:67], 0
	v_mov_b64_e32 v[68:69], 0
	v_mov_b64_e32 v[70:71], 0
	v_mov_b64_e32 v[72:73], 0
	v_mov_b64_e32 v[74:75], 0
	v_mov_b64_e32 v[76:77], 0
	v_mov_b64_e32 v[78:79], 0
	v_mov_b64_e32 v[80:81], 0
	v_mov_b64_e32 v[82:83], 0
	v_mov_b64_e32 v[84:85], 0
	v_mov_b64_e32 v[86:87], 0
	v_mov_b64_e32 v[88:89], 0
	v_mov_b64_e32 v[90:91], 0
	v_mov_b64_e32 v[92:93], 0
	v_mov_b64_e32 v[94:95], 0
	v_mov_b64_e32 v[96:97], 0
	v_mov_b64_e32 v[98:99], 0
	v_mov_b64_e32 v[100:101], 0
	v_mov_b64_e32 v[102:103], 0
	v_mov_b64_e32 v[104:105], 0
	v_mov_b64_e32 v[106:107], 0
	v_mov_b64_e32 v[108:109], 0
	v_mov_b64_e32 v[110:111], 0
	v_mov_b64_e32 v[112:113], 0
	v_mov_b64_e32 v[114:115], 0
	v_mov_b64_e32 v[116:117], 0
	v_mov_b64_e32 v[118:119], 0
	v_mov_b64_e32 v[120:121], 0
	v_mov_b64_e32 v[122:123], 0
	v_mov_b64_e32 v[124:125], 0
	v_mov_b64_e32 v[126:127], 0
	v_mov_b32_e32 v1, v0

; template <class Epi, class Sched, bool ALIGN_EPI = false, bool SP2 = false>
; __device__ __forceinline__ void gemm_phase(PG8_LAS unsigned char* lds, const Gemm g, const Sched& S, const Epi& E, const int wave_s) {
;     ...
;         const bool has_next = S.next(ui + 1, nxt);
;         const char* nA = has_next ? (const char*)g.A + (size_t)nxt.pm * tstep : cA; const char* nB = has_next ? (const char*)g.Bt + (size_t)nxt.pn * tstep : cB;
;         for (int t = 0; t < nt; t += 2) {
;             const bool last = (t == nt - 2);
;             const char* a1 = cA + (size_t)(t + 1) * kstep;
;             const char* a2 = last ? nA : cA + (size_t)(t + 2) * kstep; const char* b2 = last ? nB : cB + (size_t)(t + 2) * kstep;
;             const char* a3 = a2 + kstep; const char* b3 = b2 + kstep;
;     ...
; #pragma unroll
;         for (int a = 0; a < 2; ++a)
; #pragma unroll
;             for (int b = 0; b < 2; ++b)
; #pragma unroll
;                 for (int m = 0; m < 4; ++m)
; #pragma unroll
;                     for (int n = 0; n < 2; ++n) acc[a][b][m][n] = (f32x4){0.f, 0.f, 0.f, 0.f};
;         cur = nxt; cA = nA; cB = nB; ++ui;
.LBB0_494:
	s_ashr_i32 s11, s10, 31
	v_cmp_lt_i64_e32 vcc, s[12:13], v[172:173]
	s_lshl_b64 s[12:13], s[10:11], 19
	s_add_u32 s12, s24, s12
	s_addc_u32 s13, s25, s13
	s_and_b64 s[14:15], vcc, exec
	s_cselect_b32 s11, s13, s21
	s_cselect_b32 s44, s12, s20
	s_ashr_i32 s9, s8, 31
	s_lshl_b64 s[14:15], s[8:9], 19
	s_add_u32 s14, s26, s14
	s_addc_u32 s15, s27, s15
	s_and_b64 s[22:23], vcc, exec
	s_cselect_b32 s9, s15, s19
	s_cselect_b32 s45, s14, s18
	s_add_u32 s46, s18, 0x100
	s_addc_u32 s47, s19, 0
	s_add_u32 s18, s20, 0x40080
	v_mov_b32_e32 v0, 0
	s_addc_u32 s19, s21, 0
	s_mov_b32 s48, -2
	v_mov_b64_e32 v[2:3], 0
	v_mov_b64_e32 v[4:5], 0
	v_mov_b64_e32 v[6:7], 0
	v_mov_b64_e32 v[8:9], 0
	v_mov_b64_e32 v[10:11], 0
	v_mov_b64_e32 v[12:13], 0
	v_mov_b64_e32 v[14:15], 0
	v_mov_b64_e32 v[16:17], 0
	v_mov_b64_e32 v[18:19], 0
	v_mov_b64_e32 v[20:21], 0
	v_mov_b64_e32 v[22:23], 0
	v_mov_b64_e32 v[24:25], 0
	v_mov_b64_e32 v[26:27], 0
	v_mov_b64_e32 v[28:29], 0
	v_mov_b64_e32 v[30:31], 0
	v_mov_b64_e32 v[32:33], 0
	v_mov_b64_e32 v[34:35], 0
	v_mov_b64_e32 v[36:37], 0
	v_mov_b64_e32 v[38:39], 0
	v_mov_b64_e32 v[40:41], 0
	v_mov_b64_e32 v[42:43], 0
	v_mov_b64_e32 v[44:45], 0
	v_mov_b64_e32 v[46:47], 0
	v_mov_b64_e32 v[48:49], 0
	v_mov_b64_e32 v[50:51], 0
	v_mov_b64_e32 v[52:53], 0
	v_mov_b64_e32 v[54:55], 0
	v_mov_b64_e32 v[56:57], 0
	v_mov_b64_e32 v[58:59], 0
	v_mov_b64_e32 v[60:61], 0
	v_mov_b64_e32 v[62:63], 0
	v_mov_b64_e32 v[64:65], 0
	v_mov_b64_e32 v[66:67], 0
	v_mov_b64_e32 v[68:69], 0
	v_mov_b64_e32 v[70:71], 0
	v_mov_b64_e32 v[72:73], 0
	v_mov_b64_e32 v[74:75], 0
	v_mov_b64_e32 v[76:77], 0
	v_mov_b64_e32 v[78:79], 0
	v_mov_b64_e32 v[80:81], 0
	v_mov_b64_e32 v[82:83], 0
	v_mov_b64_e32 v[84:85], 0
	v_mov_b64_e32 v[86:87], 0
	v_mov_b64_e32 v[88:89], 0
	v_mov_b64_e32 v[90:91], 0
	v_mov_b64_e32 v[92:93], 0
	v_mov_b64_e32 v[94:95], 0
	v_mov_b64_e32 v[96:97], 0
	v_mov_b64_e32 v[98:99], 0
	v_mov_b64_e32 v[100:101], 0
	v_mov_b64_e32 v[102:103], 0
	v_mov_b64_e32 v[104:105], 0
	v_mov_b64_e32 v[106:107], 0
	v_mov_b64_e32 v[108:109], 0
	v_mov_b64_e32 v[110:111], 0
	v_mov_b64_e32 v[112:113], 0
	v_mov_b64_e32 v[114:115], 0
	v_mov_b64_e32 v[116:117], 0
	v_mov_b64_e32 v[118:119], 0
	v_mov_b64_e32 v[120:121], 0
	v_mov_b64_e32 v[122:123], 0
	v_mov_b64_e32 v[124:125], 0
	v_mov_b64_e32 v[126:127], 0
	v_mov_b32_e32 v1, v0

; template <class Epi, class Sched, bool ALIGN_EPI = false, bool SP2 = false>
; __device__ __forceinline__ void gemm_phase(PG8_LAS unsigned char* lds, const Gemm g, const Sched& S, const Epi& E, const int wave_s) {
;     ...
;         const bool has_next = S.next(ui + 1, nxt);
;         const char* nA = has_next ? (const char*)g.A + (size_t)nxt.pm * tstep : cA; const char* nB = has_next ? (const char*)g.Bt + (size_t)nxt.pn * tstep : cB;
;         for (int t = 0; t < nt; t += 2) {
;             const bool last = (t == nt - 2);
;             const char* a1 = cA + (size_t)(t + 1) * kstep;
;             const char* a2 = last ? nA : cA + (size_t)(t + 2) * kstep; const char* b2 = last ? nB : cB + (size_t)(t + 2) * kstep;
;             const char* a3 = a2 + kstep; const char* b3 = b2 + kstep;
;     ...
; #pragma unroll
;         for (int a = 0; a < 2; ++a)
; #pragma unroll
;             for (int b = 0; b < 2; ++b)
; #pragma unroll
;                 for (int m = 0; m < 4; ++m)
; #pragma unroll
;                     for (int n = 0; n < 2; ++n) acc[a][b][m][n] = (f32x4){0.f, 0.f, 0.f, 0.f};
;         cur = nxt; cA = nA; cB = nB; ++ui;
.LBB0_561:
	s_ashr_i32 s15, s14, 31
	v_cmp_lt_i64_e32 vcc, s[16:17], v[156:157]
	s_lshl_b64 s[16:17], s[14:15], 19
	s_add_u32 s16, s28, s16
	s_addc_u32 s17, s29, s17
	s_and_b64 s[18:19], vcc, exec
	s_cselect_b32 s15, s17, s23
	s_cselect_b32 s26, s16, s22
	s_ashr_i32 s13, s12, 31
	s_lshl_b64 s[18:19], s[12:13], 19
	s_add_u32 s18, s30, s18
	s_addc_u32 s19, s31, s19
	s_and_b64 s[24:25], vcc, exec
	s_cselect_b32 s13, s19, s21
	s_cselect_b32 s27, s18, s20
	s_add_u32 s55, s20, 0x100
	s_addc_u32 s56, s21, 0
	s_add_u32 s20, s22, 0x40080
	v_mov_b32_e32 v0, 0
	s_addc_u32 s21, s23, 0
	s_mov_b32 s57, -2
	v_mov_b64_e32 v[2:3], 0
	v_mov_b64_e32 v[4:5], 0
	v_mov_b64_e32 v[6:7], 0
	v_mov_b64_e32 v[8:9], 0
	v_mov_b64_e32 v[10:11], 0
	v_mov_b64_e32 v[12:13], 0
	v_mov_b64_e32 v[14:15], 0
	v_mov_b64_e32 v[16:17], 0
	v_mov_b64_e32 v[18:19], 0
	v_mov_b64_e32 v[20:21], 0
	v_mov_b64_e32 v[22:23], 0
	v_mov_b64_e32 v[24:25], 0
	v_mov_b64_e32 v[26:27], 0
	v_mov_b64_e32 v[28:29], 0
	v_mov_b64_e32 v[30:31], 0
	v_mov_b64_e32 v[32:33], 0
	v_mov_b64_e32 v[34:35], 0
	v_mov_b64_e32 v[36:37], 0
	v_mov_b64_e32 v[38:39], 0
	v_mov_b64_e32 v[40:41], 0
	v_mov_b64_e32 v[42:43], 0
	v_mov_b64_e32 v[44:45], 0
	v_mov_b64_e32 v[46:47], 0
	v_mov_b64_e32 v[48:49], 0
	v_mov_b64_e32 v[50:51], 0
	v_mov_b64_e32 v[52:53], 0
	v_mov_b64_e32 v[54:55], 0
	v_mov_b64_e32 v[56:57], 0
	v_mov_b64_e32 v[58:59], 0
	v_mov_b64_e32 v[60:61], 0
	v_mov_b64_e32 v[62:63], 0
	v_mov_b64_e32 v[64:65], 0
	v_mov_b64_e32 v[66:67], 0
	v_mov_b64_e32 v[68:69], 0
	v_mov_b64_e32 v[70:71], 0
	v_mov_b64_e32 v[72:73], 0
	v_mov_b64_e32 v[74:75], 0
	v_mov_b64_e32 v[76:77], 0
	v_mov_b64_e32 v[78:79], 0
	v_mov_b64_e32 v[80:81], 0
	v_mov_b64_e32 v[82:83], 0
	v_mov_b64_e32 v[84:85], 0
	v_mov_b64_e32 v[86:87], 0
	v_mov_b64_e32 v[88:89], 0
	v_mov_b64_e32 v[90:91], 0
	v_mov_b64_e32 v[92:93], 0
	v_mov_b64_e32 v[94:95], 0
	v_mov_b64_e32 v[96:97], 0
	v_mov_b64_e32 v[98:99], 0
	v_mov_b64_e32 v[100:101], 0
	v_mov_b64_e32 v[102:103], 0
	v_mov_b64_e32 v[104:105], 0
	v_mov_b64_e32 v[106:107], 0
	v_mov_b64_e32 v[108:109], 0
	v_mov_b64_e32 v[110:111], 0
	v_mov_b64_e32 v[112:113], 0
	v_mov_b64_e32 v[114:115], 0
	v_mov_b64_e32 v[116:117], 0
	v_mov_b64_e32 v[118:119], 0
	v_mov_b64_e32 v[120:121], 0
	v_mov_b64_e32 v[122:123], 0
	v_mov_b64_e32 v[128:129], 0
	v_mov_b64_e32 v[130:131], 0
	v_mov_b32_e32 v1, v0

; template <class Epi, class Sched, bool ALIGN_EPI = false, bool SP2 = false>
; __device__ __forceinline__ void gemm_phase(PG8_LAS unsigned char* lds, const Gemm g, const Sched& S, const Epi& E, const int wave_s) {
;     ...
;     for (;;) {
;         const bool has_next = S.next(ui + 1, nxt);
;         const char* nA = has_next ? (const char*)g.A + (size_t)nxt.pm * tstep : cA; const char* nB = has_next ? (const char*)g.Bt + (size_t)nxt.pn * tstep : cB;
;         for (int t = 0; t < nt; t += 2) {
;             const bool last = (t == nt - 2);
;             const char* a1 = cA + (size_t)(t + 1) * kstep;
;             const char* a2 = last ? nA : cA + (size_t)(t + 2) * kstep; const char* b2 = last ? nB : cB + (size_t)(t + 2) * kstep;
;             const char* a3 = a2 + kstep; const char* b3 = b2 + kstep;
;     ...
; #pragma unroll
;         for (int a = 0; a < 2; ++a)
; #pragma unroll
;             for (int b = 0; b < 2; ++b)
; #pragma unroll
;                 for (int m = 0; m < 4; ++m)
; #pragma unroll
;                     for (int n = 0; n < 2; ++n) acc[a][b][m][n] = (f32x4){0.f, 0.f, 0.f, 0.f};
;         cur = nxt; cA = nA; cB = nB; ++ui;
.LBB0_809:
	s_add_u32 s8, s28, 0x100
	v_mov_b32_e32 v0, 0
	s_addc_u32 s61, s29, 0
	s_mov_b32 s62, -2
	v_mov_b64_e32 v[2:3], 0
	v_mov_b64_e32 v[4:5], 0
	v_mov_b64_e32 v[6:7], 0
	v_mov_b64_e32 v[8:9], 0
	v_mov_b64_e32 v[10:11], 0
	v_mov_b64_e32 v[12:13], 0
	v_mov_b64_e32 v[14:15], 0
	v_mov_b64_e32 v[16:17], 0
	v_mov_b64_e32 v[18:19], 0
	v_mov_b64_e32 v[20:21], 0
	v_mov_b64_e32 v[22:23], 0
	v_mov_b64_e32 v[24:25], 0
	v_mov_b64_e32 v[26:27], 0
	v_mov_b64_e32 v[28:29], 0
	v_mov_b64_e32 v[30:31], 0
	v_mov_b64_e32 v[32:33], 0
	v_mov_b64_e32 v[34:35], 0
	v_mov_b64_e32 v[36:37], 0
	v_mov_b64_e32 v[38:39], 0
	v_mov_b64_e32 v[40:41], 0
	v_mov_b64_e32 v[42:43], 0
	v_mov_b64_e32 v[44:45], 0
	v_mov_b64_e32 v[46:47], 0
	v_mov_b64_e32 v[48:49], 0
	v_mov_b64_e32 v[50:51], 0
	v_mov_b64_e32 v[52:53], 0
	v_mov_b64_e32 v[54:55], 0
	v_mov_b64_e32 v[56:57], 0
	v_mov_b64_e32 v[58:59], 0
	v_mov_b64_e32 v[60:61], 0
	v_mov_b64_e32 v[62:63], 0
	v_mov_b64_e32 v[64:65], 0
	v_mov_b64_e32 v[66:67], 0
	v_mov_b64_e32 v[68:69], 0
	v_mov_b64_e32 v[70:71], 0
	v_mov_b64_e32 v[72:73], 0
	v_mov_b64_e32 v[74:75], 0
	v_mov_b64_e32 v[76:77], 0
	v_mov_b64_e32 v[78:79], 0
	v_mov_b64_e32 v[80:81], 0
	v_mov_b64_e32 v[82:83], 0
	v_mov_b64_e32 v[84:85], 0
	v_mov_b64_e32 v[86:87], 0
	v_mov_b64_e32 v[88:89], 0
	v_mov_b64_e32 v[90:91], 0
	v_mov_b64_e32 v[92:93], 0
	v_mov_b64_e32 v[94:95], 0
	v_mov_b64_e32 v[96:97], 0
	v_mov_b64_e32 v[98:99], 0
	v_mov_b64_e32 v[104:105], 0
	v_mov_b64_e32 v[106:107], 0
	v_mov_b64_e32 v[120:121], 0
	v_mov_b64_e32 v[122:123], 0
	v_mov_b64_e32 v[124:125], 0
	v_mov_b64_e32 v[126:127], 0
	v_mov_b64_e32 v[128:129], 0
	v_mov_b64_e32 v[130:131], 0
	v_mov_b64_e32 v[132:133], 0
	v_mov_b64_e32 v[134:135], 0
	v_mov_b64_e32 v[136:137], 0
	v_mov_b64_e32 v[138:139], 0
	v_mov_b64_e32 v[140:141], 0
	v_mov_b64_e32 v[142:143], 0
	v_mov_b32_e32 v1, v0

; template <class Epi, class Sched, bool ALIGN_EPI = false, bool SP2 = false>
; __device__ __forceinline__ void gemm_phase(PG8_LAS unsigned char* lds, const Gemm g, const Sched& S, const Epi& E, const int wave_s) {
;     ...
;         const bool has_next = S.next(ui + 1, nxt);
;         const char* nA = has_next ? (const char*)g.A + (size_t)nxt.pm * tstep : cA; const char* nB = has_next ? (const char*)g.Bt + (size_t)nxt.pn * tstep : cB;
;         for (int t = 0; t < nt; t += 2) {
;             const bool last = (t == nt - 2);
;             const char* a1 = cA + (size_t)(t + 1) * kstep;
;             const char* a2 = last ? nA : cA + (size_t)(t + 2) * kstep; const char* b2 = last ? nB : cB + (size_t)(t + 2) * kstep;
;             const char* a3 = a2 + kstep; const char* b3 = b2 + kstep;
;     ...
; #pragma unroll
;         for (int a = 0; a < 2; ++a)
; #pragma unroll
;             for (int b = 0; b < 2; ++b)
; #pragma unroll
;                 for (int m = 0; m < 4; ++m)
; #pragma unroll
;                     for (int n = 0; n < 2; ++n) acc[a][b][m][n] = (f32x4){0.f, 0.f, 0.f, 0.f};
.LBB0_959:
	s_ashr_i32 s17, s16, 31
	v_cmp_lt_i64_e32 vcc, s[18:19], v[140:141]
	s_lshl_b64 s[18:19], s[16:17], 19
	s_add_u32 s18, s30, s18
	s_addc_u32 s19, s31, s19
	s_and_b64 s[20:21], vcc, exec
	s_cselect_b32 s17, s19, s27
	s_cselect_b32 s23, s18, s26
	s_ashr_i32 s15, s14, 31
	s_lshl_b64 s[20:21], s[14:15], 19
	s_add_u32 s20, s34, s20
	s_addc_u32 s21, s35, s21
	s_and_b64 s[28:29], vcc, exec
	s_cselect_b32 s15, s21, s25
	s_cselect_b32 s51, s20, s24
	s_add_u32 s52, s24, 0x100
	s_addc_u32 s53, s25, 0
	s_add_u32 s24, s26, 0x40080
	v_mov_b32_e32 v0, 0
	s_addc_u32 s25, s27, 0
	s_mov_b32 s54, -2
	v_mov_b64_e32 v[2:3], 0
	v_mov_b64_e32 v[4:5], 0
	v_mov_b64_e32 v[6:7], 0
	v_mov_b64_e32 v[8:9], 0
	v_mov_b64_e32 v[10:11], 0
	v_mov_b64_e32 v[12:13], 0
	v_mov_b64_e32 v[14:15], 0
	v_mov_b64_e32 v[16:17], 0
	v_mov_b64_e32 v[18:19], 0
	v_mov_b64_e32 v[20:21], 0
	v_mov_b64_e32 v[22:23], 0
	v_mov_b64_e32 v[24:25], 0
	v_mov_b64_e32 v[26:27], 0
	v_mov_b64_e32 v[28:29], 0
	v_mov_b64_e32 v[30:31], 0
	v_mov_b64_e32 v[32:33], 0
	v_mov_b64_e32 v[34:35], 0
	v_mov_b64_e32 v[36:37], 0
	v_mov_b64_e32 v[38:39], 0
	v_mov_b64_e32 v[40:41], 0
	v_mov_b64_e32 v[42:43], 0
	v_mov_b64_e32 v[44:45], 0
	v_mov_b64_e32 v[46:47], 0
	v_mov_b64_e32 v[48:49], 0
	v_mov_b64_e32 v[50:51], 0
	v_mov_b64_e32 v[52:53], 0
	v_mov_b64_e32 v[54:55], 0
	v_mov_b64_e32 v[56:57], 0
	v_mov_b64_e32 v[58:59], 0
	v_mov_b64_e32 v[60:61], 0
	v_mov_b64_e32 v[62:63], 0
	v_mov_b64_e32 v[64:65], 0
	v_mov_b64_e32 v[66:67], 0
	v_mov_b64_e32 v[68:69], 0
	v_mov_b64_e32 v[70:71], 0
	v_mov_b64_e32 v[72:73], 0
	v_mov_b64_e32 v[74:75], 0
	v_mov_b64_e32 v[76:77], 0
	v_mov_b64_e32 v[78:79], 0
	v_mov_b64_e32 v[80:81], 0
	v_mov_b64_e32 v[82:83], 0
	v_mov_b64_e32 v[84:85], 0
	v_mov_b64_e32 v[86:87], 0
	v_mov_b64_e32 v[88:89], 0
	v_mov_b64_e32 v[90:91], 0
	v_mov_b64_e32 v[92:93], 0
	v_mov_b64_e32 v[94:95], 0
	v_mov_b64_e32 v[96:97], 0
	v_mov_b64_e32 v[98:99], 0
	v_mov_b64_e32 v[100:101], 0
	v_mov_b64_e32 v[102:103], 0
	v_mov_b64_e32 v[104:105], 0
	v_mov_b64_e32 v[106:107], 0
	v_mov_b64_e32 v[108:109], 0
	v_mov_b64_e32 v[110:111], 0
	v_mov_b64_e32 v[112:113], 0
	v_mov_b64_e32 v[114:115], 0
	v_mov_b64_e32 v[116:117], 0
	v_mov_b64_e32 v[118:119], 0
	v_mov_b64_e32 v[120:121], 0
	v_mov_b64_e32 v[122:123], 0
	v_mov_b64_e32 v[124:125], 0
	v_mov_b64_e32 v[126:127], 0
	v_mov_b32_e32 v1, v0

; template <class Epi, class Sched, bool ALIGN_EPI = false, bool SP2 = false>
; __device__ __forceinline__ void gemm_phase(PG8_LAS unsigned char* lds, const Gemm g, const Sched& S, const Epi& E, const int wave_s) {
;     ...
;         const bool has_next = S.next(ui + 1, nxt);
;         const char* nA = has_next ? (const char*)g.A + (size_t)nxt.pm * tstep : cA; const char* nB = has_next ? (const char*)g.Bt + (size_t)nxt.pn * tstep : cB;
;         for (int t = 0; t < nt; t += 2) {
;             const bool last = (t == nt - 2);
;             const char* a1 = cA + (size_t)(t + 1) * kstep;
;             const char* a2 = last ? nA : cA + (size_t)(t + 2) * kstep; const char* b2 = last ? nB : cB + (size_t)(t + 2) * kstep;
;             const char* a3 = a2 + kstep; const char* b3 = b2 + kstep;
;     ...
; #pragma unroll
;         for (int a = 0; a < 2; ++a)
; #pragma unroll
;             for (int b = 0; b < 2; ++b)
; #pragma unroll
;                 for (int m = 0; m < 4; ++m)
; #pragma unroll
;                     for (int n = 0; n < 2; ++n) acc[a][b][m][n] = (f32x4){0.f, 0.f, 0.f, 0.f};
.LBB0_1260:
	s_ashr_i32 s7, s6, 31
	v_cmp_lt_i64_e32 vcc, s[8:9], v[148:149]
	s_lshl_b64 s[8:9], s[6:7], 18
	s_add_u32 s8, s22, s8
	s_addc_u32 s9, s23, s9
	s_and_b64 s[10:11], vcc, exec
	s_cselect_b32 s7, s9, s17
	s_cselect_b32 s42, s8, s16
	s_ashr_i32 s5, s4, 31
	s_lshl_b64 s[10:11], s[4:5], 18
	s_add_u32 s10, s24, s10
	s_addc_u32 s11, s25, s11
	s_and_b64 s[20:21], vcc, exec
	s_cselect_b32 s5, s11, s15
	s_cselect_b32 s43, s10, s14
	s_add_u32 s44, s14, 0x100
	s_addc_u32 s45, s15, 0
	s_add_u32 s14, s16, 0x20080
	v_mov_b32_e32 v0, 0
	s_addc_u32 s15, s17, 0
	s_mov_b32 s46, -2
	v_mov_b64_e32 v[2:3], 0
	v_mov_b64_e32 v[4:5], 0
	v_mov_b64_e32 v[6:7], 0
	v_mov_b64_e32 v[8:9], 0
	v_mov_b64_e32 v[10:11], 0
	v_mov_b64_e32 v[12:13], 0
	v_mov_b64_e32 v[14:15], 0
	v_mov_b64_e32 v[16:17], 0
	v_mov_b64_e32 v[18:19], 0
	v_mov_b64_e32 v[20:21], 0
	v_mov_b64_e32 v[22:23], 0
	v_mov_b64_e32 v[24:25], 0
	v_mov_b64_e32 v[26:27], 0
	v_mov_b64_e32 v[28:29], 0
	v_mov_b64_e32 v[30:31], 0
	v_mov_b64_e32 v[32:33], 0
	v_mov_b64_e32 v[34:35], 0
	v_mov_b64_e32 v[36:37], 0
	v_mov_b64_e32 v[38:39], 0
	v_mov_b64_e32 v[40:41], 0
	v_mov_b64_e32 v[42:43], 0
	v_mov_b64_e32 v[44:45], 0
	v_mov_b64_e32 v[46:47], 0
	v_mov_b64_e32 v[48:49], 0
	v_mov_b64_e32 v[50:51], 0
	v_mov_b64_e32 v[52:53], 0
	v_mov_b64_e32 v[54:55], 0
	v_mov_b64_e32 v[56:57], 0
	v_mov_b64_e32 v[58:59], 0
	v_mov_b64_e32 v[60:61], 0
	v_mov_b64_e32 v[62:63], 0
	v_mov_b64_e32 v[64:65], 0
	v_mov_b64_e32 v[66:67], 0
	v_mov_b64_e32 v[68:69], 0
	v_mov_b64_e32 v[70:71], 0
	v_mov_b64_e32 v[72:73], 0
	v_mov_b64_e32 v[74:75], 0
	v_mov_b64_e32 v[76:77], 0
	v_mov_b64_e32 v[78:79], 0
	v_mov_b64_e32 v[80:81], 0
	v_mov_b64_e32 v[82:83], 0
	v_mov_b64_e32 v[84:85], 0
	v_mov_b64_e32 v[86:87], 0
	v_mov_b64_e32 v[88:89], 0
	v_mov_b64_e32 v[90:91], 0
	v_mov_b64_e32 v[92:93], 0
	v_mov_b64_e32 v[94:95], 0
	v_mov_b64_e32 v[96:97], 0
	v_mov_b64_e32 v[98:99], 0
	v_mov_b64_e32 v[100:101], 0
	v_mov_b64_e32 v[102:103], 0
	v_mov_b64_e32 v[104:105], 0
	v_mov_b64_e32 v[106:107], 0
	v_mov_b64_e32 v[108:109], 0
	v_mov_b64_e32 v[110:111], 0
	v_mov_b64_e32 v[112:113], 0
	v_mov_b64_e32 v[114:115], 0
	v_mov_b64_e32 v[116:117], 0
	v_mov_b64_e32 v[118:119], 0
	v_mov_b64_e32 v[120:121], 0
	v_mov_b64_e32 v[122:123], 0
	v_mov_b64_e32 v[124:125], 0
	v_mov_b64_e32 v[126:127], 0
	v_mov_b32_e32 v1, v0

; template <class Epi, class Sched, bool ALIGN_EPI = false, bool SP2 = false>
; __device__ __forceinline__ void gemm_phase(PG8_LAS unsigned char* lds, const Gemm g, const Sched& S, const Epi& E, const int wave_s) {
;     ...
;         const bool has_next = S.next(ui + 1, nxt);
;         const char* nA = has_next ? (const char*)g.A + (size_t)nxt.pm * tstep : cA; const char* nB = has_next ? (const char*)g.Bt + (size_t)nxt.pn * tstep : cB;
;         for (int t = 0; t < nt; t += 2) {
;             const bool last = (t == nt - 2);
;             const char* a1 = cA + (size_t)(t + 1) * kstep;
;             const char* a2 = last ? nA : cA + (size_t)(t + 2) * kstep; const char* b2 = last ? nB : cB + (size_t)(t + 2) * kstep;
;             const char* a3 = a2 + kstep; const char* b3 = b2 + kstep;
;     ...
; #pragma unroll
;         for (int a = 0; a < 2; ++a)
; #pragma unroll
;             for (int b = 0; b < 2; ++b)
; #pragma unroll
;                 for (int m = 0; m < 4; ++m)
; #pragma unroll
;                     for (int n = 0; n < 2; ++n) acc[a][b][m][n] = (f32x4){0.f, 0.f, 0.f, 0.f};
.LBB0_1272:
	s_ashr_i32 s9, s8, 31
	v_cmp_lt_i64_e32 vcc, s[10:11], v[172:173]
	s_lshl_b64 s[10:11], s[8:9], 19
	s_add_u32 s10, s24, s10
	s_addc_u32 s11, s25, s11
	s_and_b64 s[12:13], vcc, exec
	s_cselect_b32 s9, s11, s21
	s_cselect_b32 s44, s10, s20
	s_ashr_i32 s7, s6, 31
	s_lshl_b64 s[12:13], s[6:7], 19
	s_add_u32 s12, s26, s12
	s_addc_u32 s13, s27, s13
	s_and_b64 s[22:23], vcc, exec
	s_cselect_b32 s7, s13, s17
	s_cselect_b32 s45, s12, s16
	s_add_u32 s46, s16, 0x100
	s_addc_u32 s47, s17, 0
	s_add_u32 s16, s20, 0x40080
	v_mov_b32_e32 v0, 0
	s_addc_u32 s17, s21, 0
	s_mov_b32 s48, -2
	v_mov_b64_e32 v[2:3], 0
	v_mov_b64_e32 v[4:5], 0
	v_mov_b64_e32 v[6:7], 0
	v_mov_b64_e32 v[8:9], 0
	v_mov_b64_e32 v[10:11], 0
	v_mov_b64_e32 v[12:13], 0
	v_mov_b64_e32 v[14:15], 0
	v_mov_b64_e32 v[16:17], 0
	v_mov_b64_e32 v[18:19], 0
	v_mov_b64_e32 v[20:21], 0
	v_mov_b64_e32 v[22:23], 0
	v_mov_b64_e32 v[24:25], 0
	v_mov_b64_e32 v[26:27], 0
	v_mov_b64_e32 v[28:29], 0
	v_mov_b64_e32 v[30:31], 0
	v_mov_b64_e32 v[32:33], 0
	v_mov_b64_e32 v[34:35], 0
	v_mov_b64_e32 v[36:37], 0
	v_mov_b64_e32 v[38:39], 0
	v_mov_b64_e32 v[40:41], 0
	v_mov_b64_e32 v[42:43], 0
	v_mov_b64_e32 v[44:45], 0
	v_mov_b64_e32 v[46:47], 0
	v_mov_b64_e32 v[48:49], 0
	v_mov_b64_e32 v[50:51], 0
	v_mov_b64_e32 v[52:53], 0
	v_mov_b64_e32 v[54:55], 0
	v_mov_b64_e32 v[56:57], 0
	v_mov_b64_e32 v[58:59], 0
	v_mov_b64_e32 v[60:61], 0
	v_mov_b64_e32 v[62:63], 0
	v_mov_b64_e32 v[64:65], 0
	v_mov_b64_e32 v[66:67], 0
	v_mov_b64_e32 v[68:69], 0
	v_mov_b64_e32 v[70:71], 0
	v_mov_b64_e32 v[72:73], 0
	v_mov_b64_e32 v[74:75], 0
	v_mov_b64_e32 v[76:77], 0
	v_mov_b64_e32 v[78:79], 0
	v_mov_b64_e32 v[80:81], 0
	v_mov_b64_e32 v[82:83], 0
	v_mov_b64_e32 v[84:85], 0
	v_mov_b64_e32 v[86:87], 0
	v_mov_b64_e32 v[88:89], 0
	v_mov_b64_e32 v[90:91], 0
	v_mov_b64_e32 v[92:93], 0
	v_mov_b64_e32 v[94:95], 0
	v_mov_b64_e32 v[96:97], 0
	v_mov_b64_e32 v[98:99], 0
	v_mov_b64_e32 v[100:101], 0
	v_mov_b64_e32 v[102:103], 0
	v_mov_b64_e32 v[104:105], 0
	v_mov_b64_e32 v[106:107], 0
	v_mov_b64_e32 v[108:109], 0
	v_mov_b64_e32 v[110:111], 0
	v_mov_b64_e32 v[112:113], 0
	v_mov_b64_e32 v[114:115], 0
	v_mov_b64_e32 v[116:117], 0
	v_mov_b64_e32 v[118:119], 0
	v_mov_b64_e32 v[120:121], 0
	v_mov_b64_e32 v[122:123], 0
	v_mov_b64_e32 v[124:125], 0
	v_mov_b64_e32 v[126:127], 0
	v_mov_b32_e32 v1, v0

; template <class Epi, class Sched, bool ALIGN_EPI = false, bool SP2 = false>
; __device__ __forceinline__ void gemm_phase(PG8_LAS unsigned char* lds, const Gemm g, const Sched& S, const Epi& E, const int wave_s) {
;     ...
;         const bool has_next = S.next(ui + 1, nxt);
;         const char* nA = has_next ? (const char*)g.A + (size_t)nxt.pm * tstep : cA; const char* nB = has_next ? (const char*)g.Bt + (size_t)nxt.pn * tstep : cB;
;         for (int t = 0; t < nt; t += 2) {
;             const bool last = (t == nt - 2);
;             const char* a1 = cA + (size_t)(t + 1) * kstep;
;             const char* a2 = last ? nA : cA + (size_t)(t + 2) * kstep; const char* b2 = last ? nB : cB + (size_t)(t + 2) * kstep;
;             const char* a3 = a2 + kstep; const char* b3 = b2 + kstep;
;     ...
; #pragma unroll
;         for (int a = 0; a < 2; ++a)
; #pragma unroll
;             for (int b = 0; b < 2; ++b)
; #pragma unroll
;                 for (int m = 0; m < 4; ++m)
; #pragma unroll
;                     for (int n = 0; n < 2; ++n) acc[a][b][m][n] = (f32x4){0.f, 0.f, 0.f, 0.f};
.LBB0_1339:
	s_ashr_i32 s25, s24, 31
	v_cmp_lt_i64_e32 vcc, s[26:27], v[172:173]
	s_lshl_b64 s[26:27], s[24:25], 19
	s_add_u32 s26, s13, s26
	s_addc_u32 s27, s38, s27
	s_and_b64 s[28:29], vcc, exec
	s_cselect_b32 s25, s27, s31
	s_cselect_b32 s36, s26, s30
	s_ashr_i32 s23, s22, 31
	s_lshl_b64 s[28:29], s[22:23], 19
	s_add_u32 s28, s39, s28
	s_addc_u32 s29, s40, s29
	s_and_b64 s[34:35], vcc, exec
	s_cselect_b32 s23, s29, s21
	s_cselect_b32 s37, s28, s20
	s_add_u32 s62, s20, 0x100
	s_addc_u32 s63, s21, 0
	s_add_u32 s20, s30, 0x40080
	v_mov_b32_e32 v0, 0
	s_addc_u32 s21, s31, 0
	s_mov_b32 s64, -2
	v_mov_b64_e32 v[2:3], 0
	v_mov_b64_e32 v[4:5], 0
	v_mov_b64_e32 v[6:7], 0
	v_mov_b64_e32 v[8:9], 0
	v_mov_b64_e32 v[10:11], 0
	v_mov_b64_e32 v[12:13], 0
	v_mov_b64_e32 v[14:15], 0
	v_mov_b64_e32 v[16:17], 0
	v_mov_b64_e32 v[18:19], 0
	v_mov_b64_e32 v[20:21], 0
	v_mov_b64_e32 v[22:23], 0
	v_mov_b64_e32 v[24:25], 0
	v_mov_b64_e32 v[26:27], 0
	v_mov_b64_e32 v[28:29], 0
	v_mov_b64_e32 v[30:31], 0
	v_mov_b64_e32 v[32:33], 0
	v_mov_b64_e32 v[34:35], 0
	v_mov_b64_e32 v[36:37], 0
	v_mov_b64_e32 v[38:39], 0
	v_mov_b64_e32 v[40:41], 0
	v_mov_b64_e32 v[42:43], 0
	v_mov_b64_e32 v[44:45], 0
	v_mov_b64_e32 v[46:47], 0
	v_mov_b64_e32 v[48:49], 0
	v_mov_b64_e32 v[50:51], 0
	v_mov_b64_e32 v[52:53], 0
	v_mov_b64_e32 v[54:55], 0
	v_mov_b64_e32 v[56:57], 0
	v_mov_b64_e32 v[58:59], 0
	v_mov_b64_e32 v[60:61], 0
	v_mov_b64_e32 v[62:63], 0
	v_mov_b64_e32 v[64:65], 0
	v_mov_b64_e32 v[66:67], 0
	v_mov_b64_e32 v[68:69], 0
	v_mov_b64_e32 v[70:71], 0
	v_mov_b64_e32 v[72:73], 0
	v_mov_b64_e32 v[74:75], 0
	v_mov_b64_e32 v[76:77], 0
	v_mov_b64_e32 v[78:79], 0
	v_mov_b64_e32 v[80:81], 0
	v_mov_b64_e32 v[82:83], 0
	v_mov_b64_e32 v[84:85], 0
	v_mov_b64_e32 v[86:87], 0
	v_mov_b64_e32 v[88:89], 0
	v_mov_b64_e32 v[90:91], 0
	v_mov_b64_e32 v[92:93], 0
	v_mov_b64_e32 v[94:95], 0
	v_mov_b64_e32 v[96:97], 0
	v_mov_b64_e32 v[98:99], 0
	v_mov_b64_e32 v[104:105], 0
	v_mov_b64_e32 v[106:107], 0
	v_mov_b64_e32 v[120:121], 0
	v_mov_b64_e32 v[122:123], 0
	v_mov_b64_e32 v[124:125], 0
	v_mov_b64_e32 v[126:127], 0
	v_mov_b64_e32 v[128:129], 0
	v_mov_b64_e32 v[130:131], 0
	v_mov_b64_e32 v[132:133], 0
	v_mov_b64_e32 v[134:135], 0
	v_mov_b64_e32 v[136:137], 0
	v_mov_b64_e32 v[138:139], 0
	v_mov_b64_e32 v[140:141], 0
	v_mov_b64_e32 v[142:143], 0
	v_mov_b32_e32 v1, v0

; template <class Epi, class Sched, bool ALIGN_EPI = false, bool SP2 = false>
; __device__ __forceinline__ void gemm_phase(PG8_LAS unsigned char* lds, const Gemm g, const Sched& S, const Epi& E, const int wave_s) {
;     ...
; #pragma unroll
;         for (int a = 0; a < 2; ++a)
; #pragma unroll
;             for (int b = 0; b < 2; ++b)
; #pragma unroll
;                 for (int m = 0; m < 4; ++m)
; #pragma unroll
;                     for (int n = 0; n < 2; ++n) acc[a][b][m][n] = (f32x4){0.f, 0.f, 0.f, 0.f};
;         cur = nxt; cA = nA; cB = nB; ++ui;
.LBB0_1585:
	s_add_u32 s58, s26, 0x100
	v_mov_b32_e32 v0, 0
	s_addc_u32 s59, s27, 0
	s_mov_b32 s60, -2
	v_mov_b64_e32 v[2:3], 0
	v_mov_b64_e32 v[4:5], 0
	v_mov_b64_e32 v[6:7], 0
	v_mov_b64_e32 v[8:9], 0
	v_mov_b64_e32 v[10:11], 0
	v_mov_b64_e32 v[12:13], 0
	v_mov_b64_e32 v[14:15], 0
	v_mov_b64_e32 v[16:17], 0
	v_mov_b64_e32 v[18:19], 0
	v_mov_b64_e32 v[20:21], 0
	v_mov_b64_e32 v[22:23], 0
	v_mov_b64_e32 v[24:25], 0
	v_mov_b64_e32 v[26:27], 0
	v_mov_b64_e32 v[28:29], 0
	v_mov_b64_e32 v[30:31], 0
	v_mov_b64_e32 v[32:33], 0
	v_mov_b64_e32 v[34:35], 0
	v_mov_b64_e32 v[36:37], 0
	v_mov_b64_e32 v[38:39], 0
	v_mov_b64_e32 v[40:41], 0
	v_mov_b64_e32 v[42:43], 0
	v_mov_b64_e32 v[44:45], 0
	v_mov_b64_e32 v[46:47], 0
	v_mov_b64_e32 v[48:49], 0
	v_mov_b64_e32 v[50:51], 0
	v_mov_b64_e32 v[52:53], 0
	v_mov_b64_e32 v[54:55], 0
	v_mov_b64_e32 v[56:57], 0
	v_mov_b64_e32 v[58:59], 0
	v_mov_b64_e32 v[60:61], 0
	v_mov_b64_e32 v[62:63], 0
	v_mov_b64_e32 v[64:65], 0
	v_mov_b64_e32 v[66:67], 0
	v_mov_b64_e32 v[68:69], 0
	v_mov_b64_e32 v[70:71], 0
	v_mov_b64_e32 v[72:73], 0
	v_mov_b64_e32 v[74:75], 0
	v_mov_b64_e32 v[76:77], 0
	v_mov_b64_e32 v[78:79], 0
	v_mov_b64_e32 v[80:81], 0
	v_mov_b64_e32 v[82:83], 0
	v_mov_b64_e32 v[84:85], 0
	v_mov_b64_e32 v[86:87], 0
	v_mov_b64_e32 v[88:89], 0
	v_mov_b64_e32 v[90:91], 0
	v_mov_b64_e32 v[92:93], 0
	v_mov_b64_e32 v[94:95], 0
	v_mov_b64_e32 v[96:97], 0
	v_mov_b64_e32 v[98:99], 0
	v_mov_b64_e32 v[100:101], 0
	v_mov_b64_e32 v[102:103], 0
	v_mov_b64_e32 v[104:105], 0
	v_mov_b64_e32 v[106:107], 0
	v_mov_b64_e32 v[108:109], 0
	v_mov_b64_e32 v[110:111], 0
	v_mov_b64_e32 v[112:113], 0
	v_mov_b64_e32 v[114:115], 0
	v_mov_b64_e32 v[116:117], 0
	v_mov_b64_e32 v[118:119], 0
	v_mov_b64_e32 v[120:121], 0
	v_mov_b64_e32 v[122:123], 0
	v_mov_b64_e32 v[124:125], 0
	v_mov_b64_e32 v[126:127], 0
	v_mov_b32_e32 v1, v0

; template <class Epi, class Sched, bool ALIGN_EPI = false, bool SP2 = false>
; __device__ __forceinline__ void gemm_phase(PG8_LAS unsigned char* lds, const Gemm g, const Sched& S, const Epi& E, const int wave_s) {
;     ...
;         const bool has_next = S.next(ui + 1, nxt);
;         const char* nA = has_next ? (const char*)g.A + (size_t)nxt.pm * tstep : cA; const char* nB = has_next ? (const char*)g.Bt + (size_t)nxt.pn * tstep : cB;
;         for (int t = 0; t < nt; t += 2) {
;             const bool last = (t == nt - 2);
;             const char* a1 = cA + (size_t)(t + 1) * kstep;
;             const char* a2 = last ? nA : cA + (size_t)(t + 2) * kstep; const char* b2 = last ? nB : cB + (size_t)(t + 2) * kstep;
;             const char* a3 = a2 + kstep; const char* b3 = b2 + kstep;
;     ...
; #pragma unroll
;         for (int a = 0; a < 2; ++a)
; #pragma unroll
;             for (int b = 0; b < 2; ++b)
; #pragma unroll
;                 for (int m = 0; m < 4; ++m)
; #pragma unroll
;                     for (int n = 0; n < 2; ++n) acc[a][b][m][n] = (f32x4){0.f, 0.f, 0.f, 0.f};
.LBB0_1719:
	s_ashr_i32 s15, s14, 31
	v_cmp_lt_i64_e32 vcc, s[16:17], v[140:141]
	s_lshl_b64 s[16:17], s[14:15], 19
	s_add_u32 s16, s30, s16
	s_addc_u32 s17, s31, s17
	s_and_b64 s[20:21], vcc, exec
	s_cselect_b32 s15, s17, s27
	s_cselect_b32 s23, s16, s26
	s_ashr_i32 s13, s12, 31
	s_lshl_b64 s[20:21], s[12:13], 19
	s_add_u32 s20, s34, s20
	s_addc_u32 s21, s35, s21
	s_and_b64 s[28:29], vcc, exec
	s_cselect_b32 s13, s21, s25
	s_cselect_b32 s51, s20, s24
	s_add_u32 s52, s24, 0x100
	s_addc_u32 s53, s25, 0
	s_add_u32 s24, s26, 0x40080
	v_mov_b32_e32 v0, 0
	s_addc_u32 s25, s27, 0
	s_mov_b32 s54, -2
	v_mov_b64_e32 v[2:3], 0
	v_mov_b64_e32 v[4:5], 0
	v_mov_b64_e32 v[6:7], 0
	v_mov_b64_e32 v[8:9], 0
	v_mov_b64_e32 v[10:11], 0
	v_mov_b64_e32 v[12:13], 0
	v_mov_b64_e32 v[14:15], 0
	v_mov_b64_e32 v[16:17], 0
	v_mov_b64_e32 v[18:19], 0
	v_mov_b64_e32 v[20:21], 0
	v_mov_b64_e32 v[22:23], 0
	v_mov_b64_e32 v[24:25], 0
	v_mov_b64_e32 v[26:27], 0
	v_mov_b64_e32 v[28:29], 0
	v_mov_b64_e32 v[30:31], 0
	v_mov_b64_e32 v[32:33], 0
	v_mov_b64_e32 v[34:35], 0
	v_mov_b64_e32 v[36:37], 0
	v_mov_b64_e32 v[38:39], 0
	v_mov_b64_e32 v[40:41], 0
	v_mov_b64_e32 v[42:43], 0
	v_mov_b64_e32 v[44:45], 0
	v_mov_b64_e32 v[46:47], 0
	v_mov_b64_e32 v[48:49], 0
	v_mov_b64_e32 v[50:51], 0
	v_mov_b64_e32 v[52:53], 0
	v_mov_b64_e32 v[54:55], 0
	v_mov_b64_e32 v[56:57], 0
	v_mov_b64_e32 v[58:59], 0
	v_mov_b64_e32 v[60:61], 0
	v_mov_b64_e32 v[62:63], 0
	v_mov_b64_e32 v[64:65], 0
	v_mov_b64_e32 v[66:67], 0
	v_mov_b64_e32 v[68:69], 0
	v_mov_b64_e32 v[70:71], 0
	v_mov_b64_e32 v[72:73], 0
	v_mov_b64_e32 v[74:75], 0
	v_mov_b64_e32 v[76:77], 0
	v_mov_b64_e32 v[78:79], 0
	v_mov_b64_e32 v[80:81], 0
	v_mov_b64_e32 v[82:83], 0
	v_mov_b64_e32 v[84:85], 0
	v_mov_b64_e32 v[86:87], 0
	v_mov_b64_e32 v[88:89], 0
	v_mov_b64_e32 v[90:91], 0
	v_mov_b64_e32 v[92:93], 0
	v_mov_b64_e32 v[94:95], 0
	v_mov_b64_e32 v[96:97], 0
	v_mov_b64_e32 v[98:99], 0
	v_mov_b64_e32 v[100:101], 0
	v_mov_b64_e32 v[102:103], 0
	v_mov_b64_e32 v[104:105], 0
	v_mov_b64_e32 v[106:107], 0
	v_mov_b64_e32 v[108:109], 0
	v_mov_b64_e32 v[110:111], 0
	v_mov_b64_e32 v[112:113], 0
	v_mov_b64_e32 v[114:115], 0
	v_mov_b64_e32 v[116:117], 0
	v_mov_b64_e32 v[118:119], 0
	v_mov_b64_e32 v[120:121], 0
	v_mov_b64_e32 v[122:123], 0
	v_mov_b64_e32 v[124:125], 0
	v_mov_b64_e32 v[126:127], 0
	v_mov_b32_e32 v1, v0

; template <class Epi, class Sched, bool ALIGN_EPI = false, bool SP2 = false>
; __device__ __forceinline__ void gemm_phase(PG8_LAS unsigned char* lds, const Gemm g, const Sched& S, const Epi& E, const int wave_s) {
;     ...
;         const bool has_next = S.next(ui + 1, nxt);
;         const char* nA = has_next ? (const char*)g.A + (size_t)nxt.pm * tstep : cA; const char* nB = has_next ? (const char*)g.Bt + (size_t)nxt.pn * tstep : cB;
;         for (int t = 0; t < nt; t += 2) {
;             const bool last = (t == nt - 2);
;             const char* a1 = cA + (size_t)(t + 1) * kstep;
;             const char* a2 = last ? nA : cA + (size_t)(t + 2) * kstep; const char* b2 = last ? nB : cB + (size_t)(t + 2) * kstep;
;             const char* a3 = a2 + kstep; const char* b3 = b2 + kstep;
;     ...
; #pragma unroll
;         for (int a = 0; a < 2; ++a)
; #pragma unroll
;             for (int b = 0; b < 2; ++b)
; #pragma unroll
;                 for (int m = 0; m < 4; ++m)
; #pragma unroll
;                     for (int n = 0; n < 2; ++n) acc[a][b][m][n] = (f32x4){0.f, 0.f, 0.f, 0.f};
.LBB0_2020:
	s_ashr_i32 s7, s6, 31
	v_cmp_lt_i64_e32 vcc, s[8:9], v[148:149]
	s_lshl_b64 s[8:9], s[6:7], 18
	s_add_u32 s8, s22, s8
	s_addc_u32 s9, s23, s9
	s_and_b64 s[10:11], vcc, exec
	s_cselect_b32 s7, s9, s19
	s_cselect_b32 s42, s8, s18
	s_ashr_i32 s5, s4, 31
	s_lshl_b64 s[10:11], s[4:5], 18
	s_add_u32 s10, s24, s10
	s_addc_u32 s11, s25, s11
	s_and_b64 s[20:21], vcc, exec
	s_cselect_b32 s5, s11, s17
	s_cselect_b32 s43, s10, s16
	s_add_u32 s44, s16, 0x100
	s_addc_u32 s45, s17, 0
	s_add_u32 s16, s18, 0x20080
	v_mov_b32_e32 v0, 0
	s_addc_u32 s17, s19, 0
	s_mov_b32 s46, -2
	v_mov_b64_e32 v[2:3], 0
	v_mov_b64_e32 v[4:5], 0
	v_mov_b64_e32 v[6:7], 0
	v_mov_b64_e32 v[8:9], 0
	v_mov_b64_e32 v[10:11], 0
	v_mov_b64_e32 v[12:13], 0
	v_mov_b64_e32 v[14:15], 0
	v_mov_b64_e32 v[16:17], 0
	v_mov_b64_e32 v[18:19], 0
	v_mov_b64_e32 v[20:21], 0
	v_mov_b64_e32 v[22:23], 0
	v_mov_b64_e32 v[24:25], 0
	v_mov_b64_e32 v[26:27], 0
	v_mov_b64_e32 v[28:29], 0
	v_mov_b64_e32 v[30:31], 0
	v_mov_b64_e32 v[32:33], 0
	v_mov_b64_e32 v[34:35], 0
	v_mov_b64_e32 v[36:37], 0
	v_mov_b64_e32 v[38:39], 0
	v_mov_b64_e32 v[40:41], 0
	v_mov_b64_e32 v[42:43], 0
	v_mov_b64_e32 v[44:45], 0
	v_mov_b64_e32 v[46:47], 0
	v_mov_b64_e32 v[48:49], 0
	v_mov_b64_e32 v[50:51], 0
	v_mov_b64_e32 v[52:53], 0
	v_mov_b64_e32 v[54:55], 0
	v_mov_b64_e32 v[56:57], 0
	v_mov_b64_e32 v[58:59], 0
	v_mov_b64_e32 v[60:61], 0
	v_mov_b64_e32 v[62:63], 0
	v_mov_b64_e32 v[64:65], 0
	v_mov_b64_e32 v[66:67], 0
	v_mov_b64_e32 v[68:69], 0
	v_mov_b64_e32 v[70:71], 0
	v_mov_b64_e32 v[72:73], 0
	v_mov_b64_e32 v[74:75], 0
	v_mov_b64_e32 v[76:77], 0
	v_mov_b64_e32 v[78:79], 0
	v_mov_b64_e32 v[80:81], 0
	v_mov_b64_e32 v[82:83], 0
	v_mov_b64_e32 v[84:85], 0
	v_mov_b64_e32 v[86:87], 0
	v_mov_b64_e32 v[88:89], 0
	v_mov_b64_e32 v[90:91], 0
	v_mov_b64_e32 v[92:93], 0
	v_mov_b64_e32 v[94:95], 0
	v_mov_b64_e32 v[96:97], 0
	v_mov_b64_e32 v[98:99], 0
	v_mov_b64_e32 v[100:101], 0
	v_mov_b64_e32 v[102:103], 0
	v_mov_b64_e32 v[104:105], 0
	v_mov_b64_e32 v[106:107], 0
	v_mov_b64_e32 v[108:109], 0
	v_mov_b64_e32 v[110:111], 0
	v_mov_b64_e32 v[112:113], 0
	v_mov_b64_e32 v[114:115], 0
	v_mov_b64_e32 v[116:117], 0
	v_mov_b64_e32 v[118:119], 0
	v_mov_b64_e32 v[120:121], 0
	v_mov_b64_e32 v[122:123], 0
	v_mov_b64_e32 v[124:125], 0
	v_mov_b64_e32 v[126:127], 0
	v_mov_b32_e32 v1, v0

; template <class Epi, class Sched, bool ALIGN_EPI = false, bool SP2 = false>
; __device__ __forceinline__ void gemm_phase(PG8_LAS unsigned char* lds, const Gemm g, const Sched& S, const Epi& E, const int wave_s) {
;     ...
;         const bool has_next = S.next(ui + 1, nxt);
;         const char* nA = has_next ? (const char*)g.A + (size_t)nxt.pm * tstep : cA; const char* nB = has_next ? (const char*)g.Bt + (size_t)nxt.pn * tstep : cB;
;         for (int t = 0; t < nt; t += 2) {
;             const bool last = (t == nt - 2);
;             const char* a1 = cA + (size_t)(t + 1) * kstep;
;             const char* a2 = last ? nA : cA + (size_t)(t + 2) * kstep; const char* b2 = last ? nB : cB + (size_t)(t + 2) * kstep;
;             const char* a3 = a2 + kstep; const char* b3 = b2 + kstep;
;     ...
; #pragma unroll
;         for (int a = 0; a < 2; ++a)
; #pragma unroll
;             for (int b = 0; b < 2; ++b)
; #pragma unroll
;                 for (int m = 0; m < 4; ++m)
; #pragma unroll
;                     for (int n = 0; n < 2; ++n) acc[a][b][m][n] = (f32x4){0.f, 0.f, 0.f, 0.f};
.LBB0_2032:
	s_ashr_i32 s9, s8, 31
	v_cmp_lt_i64_e32 vcc, s[10:11], v[172:173]
	s_lshl_b64 s[10:11], s[8:9], 19
	s_add_u32 s10, s24, s10
	s_addc_u32 s11, s25, s11
	s_and_b64 s[12:13], vcc, exec
	s_cselect_b32 s9, s11, s21
	s_cselect_b32 s44, s10, s20
	s_ashr_i32 s7, s6, 31
	s_lshl_b64 s[12:13], s[6:7], 19
	s_add_u32 s12, s26, s12
	s_addc_u32 s13, s27, s13
	s_and_b64 s[22:23], vcc, exec
	s_cselect_b32 s7, s13, s19
	s_cselect_b32 s45, s12, s18
	s_add_u32 s46, s18, 0x100
	s_addc_u32 s47, s19, 0
	s_add_u32 s18, s20, 0x40080
	v_mov_b32_e32 v0, 0
	s_addc_u32 s19, s21, 0
	s_mov_b32 s48, -2
	v_mov_b64_e32 v[2:3], 0
	v_mov_b64_e32 v[4:5], 0
	v_mov_b64_e32 v[6:7], 0
	v_mov_b64_e32 v[8:9], 0
	v_mov_b64_e32 v[10:11], 0
	v_mov_b64_e32 v[12:13], 0
	v_mov_b64_e32 v[14:15], 0
	v_mov_b64_e32 v[16:17], 0
	v_mov_b64_e32 v[18:19], 0
	v_mov_b64_e32 v[20:21], 0
	v_mov_b64_e32 v[22:23], 0
	v_mov_b64_e32 v[24:25], 0
	v_mov_b64_e32 v[26:27], 0
	v_mov_b64_e32 v[28:29], 0
	v_mov_b64_e32 v[30:31], 0
	v_mov_b64_e32 v[32:33], 0
	v_mov_b64_e32 v[34:35], 0
	v_mov_b64_e32 v[36:37], 0
	v_mov_b64_e32 v[38:39], 0
	v_mov_b64_e32 v[40:41], 0
	v_mov_b64_e32 v[42:43], 0
	v_mov_b64_e32 v[44:45], 0
	v_mov_b64_e32 v[46:47], 0
	v_mov_b64_e32 v[48:49], 0
	v_mov_b64_e32 v[50:51], 0
	v_mov_b64_e32 v[52:53], 0
	v_mov_b64_e32 v[54:55], 0
	v_mov_b64_e32 v[56:57], 0
	v_mov_b64_e32 v[58:59], 0
	v_mov_b64_e32 v[60:61], 0
	v_mov_b64_e32 v[62:63], 0
	v_mov_b64_e32 v[64:65], 0
	v_mov_b64_e32 v[66:67], 0
	v_mov_b64_e32 v[68:69], 0
	v_mov_b64_e32 v[70:71], 0
	v_mov_b64_e32 v[72:73], 0
	v_mov_b64_e32 v[74:75], 0
	v_mov_b64_e32 v[76:77], 0
	v_mov_b64_e32 v[78:79], 0
	v_mov_b64_e32 v[80:81], 0
	v_mov_b64_e32 v[82:83], 0
	v_mov_b64_e32 v[84:85], 0
	v_mov_b64_e32 v[86:87], 0
	v_mov_b64_e32 v[88:89], 0
	v_mov_b64_e32 v[90:91], 0
	v_mov_b64_e32 v[92:93], 0
	v_mov_b64_e32 v[94:95], 0
	v_mov_b64_e32 v[96:97], 0
	v_mov_b64_e32 v[98:99], 0
	v_mov_b64_e32 v[100:101], 0
	v_mov_b64_e32 v[102:103], 0
	v_mov_b64_e32 v[104:105], 0
	v_mov_b64_e32 v[106:107], 0
	v_mov_b64_e32 v[108:109], 0
	v_mov_b64_e32 v[110:111], 0
	v_mov_b64_e32 v[112:113], 0
	v_mov_b64_e32 v[114:115], 0
	v_mov_b64_e32 v[116:117], 0
	v_mov_b64_e32 v[118:119], 0
	v_mov_b64_e32 v[120:121], 0
	v_mov_b64_e32 v[122:123], 0
	v_mov_b64_e32 v[124:125], 0
	v_mov_b64_e32 v[126:127], 0
	v_mov_b32_e32 v1, v0

; template <class Epi, class Sched, bool ALIGN_EPI = false, bool SP2 = false>
; __device__ __forceinline__ void gemm_phase(PG8_LAS unsigned char* lds, const Gemm g, const Sched& S, const Epi& E, const int wave_s) {
;     ...
;         const bool has_next = S.next(ui + 1, nxt);
;         const char* nA = has_next ? (const char*)g.A + (size_t)nxt.pm * tstep : cA; const char* nB = has_next ? (const char*)g.Bt + (size_t)nxt.pn * tstep : cB;
;         for (int t = 0; t < nt; t += 2) {
;             const bool last = (t == nt - 2);
;             const char* a1 = cA + (size_t)(t + 1) * kstep;
;             const char* a2 = last ? nA : cA + (size_t)(t + 2) * kstep; const char* b2 = last ? nB : cB + (size_t)(t + 2) * kstep;
;             const char* a3 = a2 + kstep; const char* b3 = b2 + kstep;
;     ...
; #pragma unroll
;         for (int a = 0; a < 2; ++a)
; #pragma unroll
;             for (int b = 0; b < 2; ++b)
; #pragma unroll
;                 for (int m = 0; m < 4; ++m)
; #pragma unroll
;                     for (int n = 0; n < 2; ++n) acc[a][b][m][n] = (f32x4){0.f, 0.f, 0.f, 0.f};
.LBB0_2099:
	v_mov_b64_e32 v[0:1], 0x440
	s_ashr_i32 s21, s20, 31
	v_cmp_lt_i64_e32 vcc, s[22:23], v[0:1]
	s_lshl_b64 s[22:23], s[20:21], 19
	s_add_u32 s22, s11, s22
	s_addc_u32 s23, s36, s23
	s_and_b64 s[24:25], vcc, exec
	s_cselect_b32 s21, s23, s29
	s_cselect_b32 s34, s22, s28
	s_ashr_i32 s19, s18, 31
	s_lshl_b64 s[24:25], s[18:19], 19
	s_add_u32 s24, s37, s24
	s_addc_u32 s25, s38, s25
	s_and_b64 s[30:31], vcc, exec
	s_cselect_b32 s19, s25, s27
	s_cselect_b32 s35, s24, s26
	s_add_u32 s60, s26, 0x100
	s_addc_u32 s61, s27, 0
	s_add_u32 s26, s28, 0x40080
	v_mov_b32_e32 v0, 0
	s_addc_u32 s27, s29, 0
	s_mov_b32 s62, -2
	v_mov_b64_e32 v[2:3], 0
	v_mov_b64_e32 v[4:5], 0
	v_mov_b64_e32 v[6:7], 0
	v_mov_b64_e32 v[8:9], 0
	v_mov_b64_e32 v[10:11], 0
	v_mov_b64_e32 v[12:13], 0
	v_mov_b64_e32 v[14:15], 0
	v_mov_b64_e32 v[16:17], 0
	v_mov_b64_e32 v[18:19], 0
	v_mov_b64_e32 v[20:21], 0
	v_mov_b64_e32 v[22:23], 0
	v_mov_b64_e32 v[24:25], 0
	v_mov_b64_e32 v[26:27], 0
	v_mov_b64_e32 v[28:29], 0
	v_mov_b64_e32 v[30:31], 0
	v_mov_b64_e32 v[32:33], 0
	v_mov_b64_e32 v[34:35], 0
	v_mov_b64_e32 v[36:37], 0
	v_mov_b64_e32 v[38:39], 0
	v_mov_b64_e32 v[40:41], 0
	v_mov_b64_e32 v[42:43], 0
	v_mov_b64_e32 v[44:45], 0
	v_mov_b64_e32 v[46:47], 0
	v_mov_b64_e32 v[48:49], 0
	v_mov_b64_e32 v[50:51], 0
	v_mov_b64_e32 v[52:53], 0
	v_mov_b64_e32 v[54:55], 0
	v_mov_b64_e32 v[56:57], 0
	v_mov_b64_e32 v[58:59], 0
	v_mov_b64_e32 v[60:61], 0
	v_mov_b64_e32 v[62:63], 0
	v_mov_b64_e32 v[64:65], 0
	v_mov_b64_e32 v[66:67], 0
	v_mov_b64_e32 v[68:69], 0
	v_mov_b64_e32 v[70:71], 0
	v_mov_b64_e32 v[72:73], 0
	v_mov_b64_e32 v[74:75], 0
	v_mov_b64_e32 v[76:77], 0
	v_mov_b64_e32 v[78:79], 0
	v_mov_b64_e32 v[80:81], 0
	v_mov_b64_e32 v[82:83], 0
	v_mov_b64_e32 v[84:85], 0
	v_mov_b64_e32 v[86:87], 0
	v_mov_b64_e32 v[88:89], 0
	v_mov_b64_e32 v[90:91], 0
	v_mov_b64_e32 v[92:93], 0
	v_mov_b64_e32 v[94:95], 0
	v_mov_b64_e32 v[96:97], 0
	v_mov_b64_e32 v[98:99], 0
	v_mov_b64_e32 v[100:101], 0
	v_mov_b64_e32 v[102:103], 0
	v_mov_b64_e32 v[104:105], 0
	v_mov_b64_e32 v[106:107], 0
	v_mov_b64_e32 v[108:109], 0
	v_mov_b64_e32 v[110:111], 0
	v_mov_b64_e32 v[112:113], 0
	v_mov_b64_e32 v[114:115], 0
	v_mov_b64_e32 v[116:117], 0
	v_mov_b64_e32 v[118:119], 0
	v_mov_b64_e32 v[120:121], 0
	v_mov_b64_e32 v[122:123], 0
	v_mov_b64_e32 v[124:125], 0
	v_mov_b64_e32 v[126:127], 0
	v_mov_b32_e32 v1, v0

; template <class Epi, class Sched, bool ALIGN_EPI = false, bool SP2 = false>
; __device__ __forceinline__ void gemm_phase(PG8_LAS unsigned char* lds, const Gemm g, const Sched& S, const Epi& E, const int wave_s) {
;     ...
;         const bool has_next = S.next(ui + 1, nxt);
;         const char* nA = has_next ? (const char*)g.A + (size_t)nxt.pm * tstep : cA; const char* nB = has_next ? (const char*)g.Bt + (size_t)nxt.pn * tstep : cB;
;         for (int t = 0; t < nt; t += 2) {
;             const bool last = (t == nt - 2);
;             const char* a1 = cA + (size_t)(t + 1) * kstep;
;             const char* a2 = last ? nA : cA + (size_t)(t + 2) * kstep; const char* b2 = last ? nB : cB + (size_t)(t + 2) * kstep;
;             const char* a3 = a2 + kstep; const char* b3 = b2 + kstep;
;     ...
; #pragma unroll
;         for (int a = 0; a < 2; ++a)
; #pragma unroll
;             for (int b = 0; b < 2; ++b)
; #pragma unroll
;                 for (int m = 0; m < 4; ++m)
; #pragma unroll
;                     for (int n = 0; n < 2; ++n) acc[a][b][m][n] = (f32x4){0.f, 0.f, 0.f, 0.f};
.LBB0_2235:
	s_ashr_i32 s49, s48, 31
	s_lshl_b64 s[50:51], s[48:49], 19
	s_add_u32 s50, s31, s50
	s_addc_u32 s51, s35, s51
	s_and_b64 s[52:53], s[8:9], exec
	s_cselect_b32 s15, s51, s21
	s_cselect_b32 s17, s50, s20
	s_ashr_i32 s47, s46, 31
	s_lshl_b64 s[52:53], s[46:47], 19
	s_add_u32 s52, s37, s52
	s_addc_u32 s53, s39, s53
	s_and_b64 s[54:55], s[8:9], exec
	s_cselect_b32 s47, s53, s19
	s_cselect_b32 s49, s52, s18
	s_add_u32 s56, s18, 0x100
	s_addc_u32 s57, s19, 0
	s_add_u32 s18, s20, 0x40080
	v_mov_b32_e32 v0, 0
	s_addc_u32 s19, s21, 0
	s_mov_b32 s74, -2
	v_mov_b64_e32 v[2:3], 0
	v_mov_b64_e32 v[4:5], 0
	v_mov_b64_e32 v[6:7], 0
	v_mov_b64_e32 v[8:9], 0
	v_mov_b64_e32 v[10:11], 0
	v_mov_b64_e32 v[12:13], 0
	v_mov_b64_e32 v[14:15], 0
	v_mov_b64_e32 v[16:17], 0
	v_mov_b64_e32 v[18:19], 0
	v_mov_b64_e32 v[20:21], 0
	v_mov_b64_e32 v[22:23], 0
	v_mov_b64_e32 v[24:25], 0
	v_mov_b64_e32 v[26:27], 0
	v_mov_b64_e32 v[28:29], 0
	v_mov_b64_e32 v[30:31], 0
	v_mov_b64_e32 v[32:33], 0
	v_mov_b64_e32 v[34:35], 0
	v_mov_b64_e32 v[36:37], 0
	v_mov_b64_e32 v[38:39], 0
	v_mov_b64_e32 v[40:41], 0
	v_mov_b64_e32 v[42:43], 0
	v_mov_b64_e32 v[44:45], 0
	v_mov_b64_e32 v[46:47], 0
	v_mov_b64_e32 v[48:49], 0
	v_mov_b64_e32 v[50:51], 0
	v_mov_b64_e32 v[52:53], 0
	v_mov_b64_e32 v[54:55], 0
	v_mov_b64_e32 v[72:73], 0
	v_mov_b64_e32 v[74:75], 0
	v_mov_b64_e32 v[76:77], 0
	v_mov_b64_e32 v[78:79], 0
	v_mov_b64_e32 v[80:81], 0
	v_mov_b64_e32 v[82:83], 0
	v_mov_b64_e32 v[84:85], 0
	v_mov_b64_e32 v[86:87], 0
	v_mov_b64_e32 v[88:89], 0
	v_mov_b64_e32 v[90:91], 0
	v_mov_b64_e32 v[92:93], 0
	v_mov_b64_e32 v[94:95], 0
	v_mov_b64_e32 v[96:97], 0
	v_mov_b64_e32 v[98:99], 0
	v_mov_b64_e32 v[116:117], 0
	v_mov_b64_e32 v[118:119], 0
	v_mov_b64_e32 v[120:121], 0
	v_mov_b64_e32 v[122:123], 0
	v_mov_b64_e32 v[124:125], 0
	v_mov_b64_e32 v[126:127], 0
	v_mov_b64_e32 v[128:129], 0
	v_mov_b64_e32 v[130:131], 0
	v_mov_b64_e32 v[132:133], 0
	v_mov_b64_e32 v[134:135], 0
	v_mov_b64_e32 v[136:137], 0
	v_mov_b64_e32 v[138:139], 0
	v_mov_b64_e32 v[140:141], 0
	v_mov_b64_e32 v[142:143], 0
	v_mov_b64_e32 v[144:145], 0
	v_mov_b64_e32 v[146:147], 0
	v_mov_b64_e32 v[148:149], 0
	v_mov_b64_e32 v[150:151], 0
	v_mov_b64_e32 v[152:153], 0
	v_mov_b64_e32 v[154:155], 0
	v_mov_b64_e32 v[156:157], 0
	v_mov_b64_e32 v[158:159], 0
	v_mov_b32_e32 v1, v0

; template <class Epi, class Sched, bool ALIGN_EPI = false, bool SP2 = false>
; __device__ __forceinline__ void gemm_phase(PG8_LAS unsigned char* lds, const Gemm g, const Sched& S, const Epi& E, const int wave_s) {
;     ...
; #pragma unroll
;         for (int a = 0; a < 2; ++a)
; #pragma unroll
;             for (int b = 0; b < 2; ++b)
; #pragma unroll
;                 for (int m = 0; m < 4; ++m)
; #pragma unroll
;                     for (int n = 0; n < 2; ++n) acc[a][b][m][n] = (f32x4){0.f, 0.f, 0.f, 0.f};
;         cur = nxt; cA = nA; cB = nB; ++ui;
.LBB0_2337:
	s_add_u32 s58, s24, 0x100
	v_mov_b32_e32 v0, 0
	s_addc_u32 s59, s25, 0
	s_mov_b32 s60, -2
	v_mov_b64_e32 v[2:3], 0
	v_mov_b64_e32 v[4:5], 0
	v_mov_b64_e32 v[6:7], 0
	v_mov_b64_e32 v[8:9], 0
	v_mov_b64_e32 v[10:11], 0
	v_mov_b64_e32 v[12:13], 0
	v_mov_b64_e32 v[14:15], 0
	v_mov_b64_e32 v[16:17], 0
	v_mov_b64_e32 v[18:19], 0
	v_mov_b64_e32 v[20:21], 0
	v_mov_b64_e32 v[22:23], 0
	v_mov_b64_e32 v[24:25], 0
	v_mov_b64_e32 v[26:27], 0
	v_mov_b64_e32 v[28:29], 0
	v_mov_b64_e32 v[30:31], 0
	v_mov_b64_e32 v[32:33], 0
	v_mov_b64_e32 v[34:35], 0
	v_mov_b64_e32 v[36:37], 0
	v_mov_b64_e32 v[38:39], 0
	v_mov_b64_e32 v[40:41], 0
	v_mov_b64_e32 v[42:43], 0
	v_mov_b64_e32 v[44:45], 0
	v_mov_b64_e32 v[46:47], 0
	v_mov_b64_e32 v[48:49], 0
	v_mov_b64_e32 v[50:51], 0
	v_mov_b64_e32 v[52:53], 0
	v_mov_b64_e32 v[54:55], 0
	v_mov_b64_e32 v[56:57], 0
	v_mov_b64_e32 v[58:59], 0
	v_mov_b64_e32 v[60:61], 0
	v_mov_b64_e32 v[62:63], 0
	v_mov_b64_e32 v[64:65], 0
	v_mov_b64_e32 v[66:67], 0
	v_mov_b64_e32 v[68:69], 0
	v_mov_b64_e32 v[70:71], 0
	v_mov_b64_e32 v[72:73], 0
	v_mov_b64_e32 v[74:75], 0
	v_mov_b64_e32 v[76:77], 0
	v_mov_b64_e32 v[78:79], 0
	v_mov_b64_e32 v[80:81], 0
	v_mov_b64_e32 v[82:83], 0
	v_mov_b64_e32 v[84:85], 0
	v_mov_b64_e32 v[86:87], 0
	v_mov_b64_e32 v[88:89], 0
	v_mov_b64_e32 v[90:91], 0
	v_mov_b64_e32 v[92:93], 0
	v_mov_b64_e32 v[94:95], 0
	v_mov_b64_e32 v[96:97], 0
	v_mov_b64_e32 v[98:99], 0
	v_mov_b64_e32 v[100:101], 0
	v_mov_b64_e32 v[102:103], 0
	v_mov_b64_e32 v[104:105], 0
	v_mov_b64_e32 v[106:107], 0
	v_mov_b64_e32 v[108:109], 0
	v_mov_b64_e32 v[110:111], 0
	v_mov_b64_e32 v[112:113], 0
	v_mov_b64_e32 v[114:115], 0
	v_mov_b64_e32 v[116:117], 0
	v_mov_b64_e32 v[118:119], 0
	v_mov_b64_e32 v[120:121], 0
	v_mov_b64_e32 v[122:123], 0
	v_mov_b64_e32 v[124:125], 0
	v_mov_b64_e32 v[126:127], 0
	v_mov_b32_e32 v1, v0

; template <class Epi, class Sched, bool ALIGN_EPI = false, bool SP2 = false>
; __device__ __forceinline__ void gemm_phase(PG8_LAS unsigned char* lds, const Gemm g, const Sched& S, const Epi& E, const int wave_s) {
;     ...
;         const bool has_next = S.next(ui + 1, nxt);
;         const char* nA = has_next ? (const char*)g.A + (size_t)nxt.pm * tstep : cA; const char* nB = has_next ? (const char*)g.Bt + (size_t)nxt.pn * tstep : cB;
;         for (int t = 0; t < nt; t += 2) {
;             const bool last = (t == nt - 2);
;             const char* a1 = cA + (size_t)(t + 1) * kstep;
;             const char* a2 = last ? nA : cA + (size_t)(t + 2) * kstep; const char* b2 = last ? nB : cB + (size_t)(t + 2) * kstep;
;             const char* a3 = a2 + kstep; const char* b3 = b2 + kstep;
;     ...
; #pragma unroll
;         for (int a = 0; a < 2; ++a)
; #pragma unroll
;             for (int b = 0; b < 2; ++b)
; #pragma unroll
;                 for (int m = 0; m < 4; ++m)
; #pragma unroll
;                     for (int n = 0; n < 2; ++n) acc[a][b][m][n] = (f32x4){0.f, 0.f, 0.f, 0.f};
.LBB0_2780:
	s_ashr_i32 s11, s10, 31
	v_cmp_lt_i64_e32 vcc, s[12:13], v[148:149]
	s_lshl_b64 s[12:13], s[10:11], 18
	s_add_u32 s12, s25, s12
	s_addc_u32 s13, s26, s13
	s_and_b64 s[14:15], vcc, exec
	s_cselect_b32 s11, s13, s21
	s_cselect_b32 s43, s12, s20
	s_ashr_i32 s9, s8, 31
	s_lshl_b64 s[14:15], s[8:9], 18
	s_add_u32 s14, s27, s14
	s_addc_u32 s15, s28, s15
	s_and_b64 s[22:23], vcc, exec
	s_cselect_b32 s9, s15, s19
	s_cselect_b32 s44, s14, s18
	s_add_u32 s45, s18, 0x100
	s_addc_u32 s46, s19, 0
	s_add_u32 s18, s20, 0x20080
	v_mov_b32_e32 v0, 0
	s_addc_u32 s19, s21, 0
	s_mov_b32 s47, -2
	v_mov_b64_e32 v[2:3], 0
	v_mov_b64_e32 v[4:5], 0
	v_mov_b64_e32 v[6:7], 0
	v_mov_b64_e32 v[8:9], 0
	v_mov_b64_e32 v[10:11], 0
	v_mov_b64_e32 v[12:13], 0
	v_mov_b64_e32 v[14:15], 0
	v_mov_b64_e32 v[16:17], 0
	v_mov_b64_e32 v[18:19], 0
	v_mov_b64_e32 v[20:21], 0
	v_mov_b64_e32 v[22:23], 0
	v_mov_b64_e32 v[24:25], 0
	v_mov_b64_e32 v[26:27], 0
	v_mov_b64_e32 v[28:29], 0
	v_mov_b64_e32 v[30:31], 0
	v_mov_b64_e32 v[32:33], 0
	v_mov_b64_e32 v[34:35], 0
	v_mov_b64_e32 v[36:37], 0
	v_mov_b64_e32 v[38:39], 0
	v_mov_b64_e32 v[40:41], 0
	v_mov_b64_e32 v[42:43], 0
	v_mov_b64_e32 v[44:45], 0
	v_mov_b64_e32 v[46:47], 0
	v_mov_b64_e32 v[48:49], 0
	v_mov_b64_e32 v[50:51], 0
	v_mov_b64_e32 v[52:53], 0
	v_mov_b64_e32 v[54:55], 0
	v_mov_b64_e32 v[56:57], 0
	v_mov_b64_e32 v[58:59], 0
	v_mov_b64_e32 v[60:61], 0
	v_mov_b64_e32 v[62:63], 0
	v_mov_b64_e32 v[64:65], 0
	v_mov_b64_e32 v[66:67], 0
	v_mov_b64_e32 v[68:69], 0
	v_mov_b64_e32 v[70:71], 0
	v_mov_b64_e32 v[72:73], 0
	v_mov_b64_e32 v[74:75], 0
	v_mov_b64_e32 v[76:77], 0
	v_mov_b64_e32 v[78:79], 0
	v_mov_b64_e32 v[80:81], 0
	v_mov_b64_e32 v[82:83], 0
	v_mov_b64_e32 v[84:85], 0
	v_mov_b64_e32 v[86:87], 0
	v_mov_b64_e32 v[88:89], 0
	v_mov_b64_e32 v[90:91], 0
	v_mov_b64_e32 v[92:93], 0
	v_mov_b64_e32 v[94:95], 0
	v_mov_b64_e32 v[96:97], 0
	v_mov_b64_e32 v[98:99], 0
	v_mov_b64_e32 v[100:101], 0
	v_mov_b64_e32 v[102:103], 0
	v_mov_b64_e32 v[104:105], 0
	v_mov_b64_e32 v[106:107], 0
	v_mov_b64_e32 v[108:109], 0
	v_mov_b64_e32 v[110:111], 0
	v_mov_b64_e32 v[112:113], 0
	v_mov_b64_e32 v[114:115], 0
	v_mov_b64_e32 v[116:117], 0
	v_mov_b64_e32 v[118:119], 0
	v_mov_b64_e32 v[120:121], 0
	v_mov_b64_e32 v[122:123], 0
	v_mov_b64_e32 v[124:125], 0
	v_mov_b64_e32 v[126:127], 0
	v_mov_b32_e32 v1, v0

; template <class Epi, class Sched, bool ALIGN_EPI = false, bool SP2 = false>
; __device__ __forceinline__ void gemm_phase(PG8_LAS unsigned char* lds, const Gemm g, const Sched& S, const Epi& E, const int wave_s) {
;     ...
;         const bool has_next = S.next(ui + 1, nxt);
;         const char* nA = has_next ? (const char*)g.A + (size_t)nxt.pm * tstep : cA; const char* nB = has_next ? (const char*)g.Bt + (size_t)nxt.pn * tstep : cB;
;         for (int t = 0; t < nt; t += 2) {
;             const bool last = (t == nt - 2);
;             const char* a1 = cA + (size_t)(t + 1) * kstep;
;             const char* a2 = last ? nA : cA + (size_t)(t + 2) * kstep; const char* b2 = last ? nB : cB + (size_t)(t + 2) * kstep;
;             const char* a3 = a2 + kstep; const char* b3 = b2 + kstep;
;     ...
; #pragma unroll
;         for (int a = 0; a < 2; ++a)
; #pragma unroll
;             for (int b = 0; b < 2; ++b)
; #pragma unroll
;                 for (int m = 0; m < 4; ++m)
; #pragma unroll
;                     for (int n = 0; n < 2; ++n) acc[a][b][m][n] = (f32x4){0.f, 0.f, 0.f, 0.f};
.LBB0_2800:
	s_ashr_i32 s13, s12, 31
	v_cmp_lt_i64_e32 vcc, s[14:15], v[172:173]
	s_lshl_b64 s[14:15], s[12:13], 19
	s_add_u32 s14, s27, s14
	s_addc_u32 s15, s28, s15
	s_and_b64 s[16:17], vcc, exec
	s_cselect_b32 s13, s15, s23
	s_cselect_b32 s45, s14, s22
	s_ashr_i32 s11, s10, 31
	s_lshl_b64 s[16:17], s[10:11], 19
	s_add_u32 s16, s29, s16
	s_addc_u32 s17, s30, s17
	s_and_b64 s[24:25], vcc, exec
	s_cselect_b32 s11, s17, s21
	s_cselect_b32 s46, s16, s20
	s_add_u32 s47, s20, 0x100
	s_addc_u32 s48, s21, 0
	s_add_u32 s20, s22, 0x40080
	v_mov_b32_e32 v0, 0
	s_addc_u32 s21, s23, 0
	s_mov_b32 s49, -2
	v_mov_b64_e32 v[2:3], 0
	v_mov_b64_e32 v[4:5], 0
	v_mov_b64_e32 v[6:7], 0
	v_mov_b64_e32 v[8:9], 0
	v_mov_b64_e32 v[10:11], 0
	v_mov_b64_e32 v[12:13], 0
	v_mov_b64_e32 v[14:15], 0
	v_mov_b64_e32 v[16:17], 0
	v_mov_b64_e32 v[18:19], 0
	v_mov_b64_e32 v[20:21], 0
	v_mov_b64_e32 v[22:23], 0
	v_mov_b64_e32 v[24:25], 0
	v_mov_b64_e32 v[26:27], 0
	v_mov_b64_e32 v[28:29], 0
	v_mov_b64_e32 v[30:31], 0
	v_mov_b64_e32 v[32:33], 0
	v_mov_b64_e32 v[34:35], 0
	v_mov_b64_e32 v[36:37], 0
	v_mov_b64_e32 v[38:39], 0
	v_mov_b64_e32 v[40:41], 0
	v_mov_b64_e32 v[42:43], 0
	v_mov_b64_e32 v[44:45], 0
	v_mov_b64_e32 v[46:47], 0
	v_mov_b64_e32 v[48:49], 0
	v_mov_b64_e32 v[50:51], 0
	v_mov_b64_e32 v[52:53], 0
	v_mov_b64_e32 v[54:55], 0
	v_mov_b64_e32 v[56:57], 0
	v_mov_b64_e32 v[58:59], 0
	v_mov_b64_e32 v[60:61], 0
	v_mov_b64_e32 v[62:63], 0
	v_mov_b64_e32 v[64:65], 0
	v_mov_b64_e32 v[66:67], 0
	v_mov_b64_e32 v[68:69], 0
	v_mov_b64_e32 v[70:71], 0
	v_mov_b64_e32 v[72:73], 0
	v_mov_b64_e32 v[74:75], 0
	v_mov_b64_e32 v[76:77], 0
	v_mov_b64_e32 v[78:79], 0
	v_mov_b64_e32 v[80:81], 0
	v_mov_b64_e32 v[82:83], 0
	v_mov_b64_e32 v[84:85], 0
	v_mov_b64_e32 v[86:87], 0
	v_mov_b64_e32 v[88:89], 0
	v_mov_b64_e32 v[90:91], 0
	v_mov_b64_e32 v[92:93], 0
	v_mov_b64_e32 v[94:95], 0
	v_mov_b64_e32 v[96:97], 0
	v_mov_b64_e32 v[98:99], 0
	v_mov_b64_e32 v[100:101], 0
	v_mov_b64_e32 v[102:103], 0
	v_mov_b64_e32 v[104:105], 0
	v_mov_b64_e32 v[106:107], 0
	v_mov_b64_e32 v[108:109], 0
	v_mov_b64_e32 v[110:111], 0
	v_mov_b64_e32 v[112:113], 0
	v_mov_b64_e32 v[114:115], 0
	v_mov_b64_e32 v[116:117], 0
	v_mov_b64_e32 v[118:119], 0
	v_mov_b64_e32 v[120:121], 0
	v_mov_b64_e32 v[122:123], 0
	v_mov_b64_e32 v[124:125], 0
	v_mov_b64_e32 v[126:127], 0
	v_mov_b32_e32 v1, v0

; template <class Epi, class Sched, bool ALIGN_EPI = false, bool SP2 = false>
; __device__ __forceinline__ void gemm_phase(PG8_LAS unsigned char* lds, const Gemm g, const Sched& S, const Epi& E, const int wave_s) {
;     ...
;         const bool has_next = S.next(ui + 1, nxt);
;         const char* nA = has_next ? (const char*)g.A + (size_t)nxt.pm * tstep : cA; const char* nB = has_next ? (const char*)g.Bt + (size_t)nxt.pn * tstep : cB;
;         for (int t = 0; t < nt; t += 2) {
;             const bool last = (t == nt - 2);
;             const char* a1 = cA + (size_t)(t + 1) * kstep;
;             const char* a2 = last ? nA : cA + (size_t)(t + 2) * kstep; const char* b2 = last ? nB : cB + (size_t)(t + 2) * kstep;
;             const char* a3 = a2 + kstep; const char* b3 = b2 + kstep;
;     ...
; #pragma unroll
;         for (int a = 0; a < 2; ++a)
; #pragma unroll
;             for (int b = 0; b < 2; ++b)
; #pragma unroll
;                 for (int m = 0; m < 4; ++m)
; #pragma unroll
;                     for (int n = 0; n < 2; ++n) acc[a][b][m][n] = (f32x4){0.f, 0.f, 0.f, 0.f};
.LBB0_2875:
	v_mov_b64_e32 v[0:1], 0x400
	s_ashr_i32 s23, s22, 31
	v_cmp_lt_i64_e32 vcc, s[24:25], v[0:1]
	s_lshl_b64 s[24:25], s[22:23], 19
	s_add_u32 s24, s39, s24
	s_addc_u32 s25, s40, s25
	s_and_b64 s[26:27], vcc, exec
	s_cselect_b32 s23, s25, s31
	s_cselect_b32 s36, s24, s30
	s_ashr_i32 s21, s20, 31
	s_lshl_b64 s[26:27], s[20:21], 19
	s_add_u32 s26, s41, s26
	s_addc_u32 s27, s42, s27
	s_and_b64 s[34:35], vcc, exec
	s_cselect_b32 s21, s27, s29
	s_cselect_b32 s37, s26, s28
	s_add_u32 s61, s28, 0x100
	s_addc_u32 s62, s29, 0
	s_add_u32 s28, s30, 0x40080
	v_mov_b32_e32 v0, 0
	s_addc_u32 s29, s31, 0
	s_mov_b32 s63, -2
	v_mov_b64_e32 v[2:3], 0
	v_mov_b64_e32 v[4:5], 0
	v_mov_b64_e32 v[6:7], 0
	v_mov_b64_e32 v[8:9], 0
	v_mov_b64_e32 v[10:11], 0
	v_mov_b64_e32 v[12:13], 0
	v_mov_b64_e32 v[14:15], 0
	v_mov_b64_e32 v[16:17], 0
	v_mov_b64_e32 v[18:19], 0
	v_mov_b64_e32 v[20:21], 0
	v_mov_b64_e32 v[22:23], 0
	v_mov_b64_e32 v[24:25], 0
	v_mov_b64_e32 v[26:27], 0
	v_mov_b64_e32 v[28:29], 0
	v_mov_b64_e32 v[30:31], 0
	v_mov_b64_e32 v[32:33], 0
	v_mov_b64_e32 v[34:35], 0
	v_mov_b64_e32 v[36:37], 0
	v_mov_b64_e32 v[38:39], 0
	v_mov_b64_e32 v[40:41], 0
	v_mov_b64_e32 v[42:43], 0
	v_mov_b64_e32 v[44:45], 0
	v_mov_b64_e32 v[46:47], 0
	v_mov_b64_e32 v[48:49], 0
	v_mov_b64_e32 v[50:51], 0
	v_mov_b64_e32 v[52:53], 0
	v_mov_b64_e32 v[54:55], 0
	v_mov_b64_e32 v[56:57], 0
	v_mov_b64_e32 v[58:59], 0
	v_mov_b64_e32 v[60:61], 0
	v_mov_b64_e32 v[62:63], 0
	v_mov_b64_e32 v[64:65], 0
	v_mov_b64_e32 v[66:67], 0
	v_mov_b64_e32 v[68:69], 0
	v_mov_b64_e32 v[70:71], 0
	v_mov_b64_e32 v[72:73], 0
	v_mov_b64_e32 v[74:75], 0
	v_mov_b64_e32 v[76:77], 0
	v_mov_b64_e32 v[78:79], 0
	v_mov_b64_e32 v[80:81], 0
	v_mov_b64_e32 v[82:83], 0
	v_mov_b64_e32 v[84:85], 0
	v_mov_b64_e32 v[86:87], 0
	v_mov_b64_e32 v[88:89], 0
	v_mov_b64_e32 v[90:91], 0
	v_mov_b64_e32 v[92:93], 0
	v_mov_b64_e32 v[94:95], 0
	v_mov_b64_e32 v[96:97], 0
	v_mov_b64_e32 v[98:99], 0
	v_mov_b64_e32 v[100:101], 0
	v_mov_b64_e32 v[102:103], 0
	v_mov_b64_e32 v[104:105], 0
	v_mov_b64_e32 v[106:107], 0
	v_mov_b64_e32 v[108:109], 0
	v_mov_b64_e32 v[110:111], 0
	v_mov_b64_e32 v[112:113], 0
	v_mov_b64_e32 v[114:115], 0
	v_mov_b64_e32 v[116:117], 0
	v_mov_b64_e32 v[118:119], 0
	v_mov_b64_e32 v[120:121], 0
	v_mov_b64_e32 v[122:123], 0
	v_mov_b64_e32 v[124:125], 0
	v_mov_b64_e32 v[126:127], 0
	v_mov_b32_e32 v1, v0

; template <class Epi, class Sched, bool ALIGN_EPI = false, bool SP2 = false>
; __device__ __forceinline__ void gemm_phase(PG8_LAS unsigned char* lds, const Gemm g, const Sched& S, const Epi& E, const int wave_s) {
;     ...
;         const bool has_next = S.next(ui + 1, nxt);
;         const char* nA = has_next ? (const char*)g.A + (size_t)nxt.pm * tstep : cA; const char* nB = has_next ? (const char*)g.Bt + (size_t)nxt.pn * tstep : cB;
;         for (int t = 0; t < nt; t += 2) {
;             const bool last = (t == nt - 2);
;             const char* a1 = cA + (size_t)(t + 1) * kstep;
;             const char* a2 = last ? nA : cA + (size_t)(t + 2) * kstep; const char* b2 = last ? nB : cB + (size_t)(t + 2) * kstep;
;             const char* a3 = a2 + kstep; const char* b3 = b2 + kstep;
;     ...
; #pragma unroll
;         for (int a = 0; a < 2; ++a)
; #pragma unroll
;             for (int b = 0; b < 2; ++b)
; #pragma unroll
;                 for (int m = 0; m < 4; ++m)
; #pragma unroll
;                     for (int n = 0; n < 2; ++n) acc[a][b][m][n] = (f32x4){0.f, 0.f, 0.f, 0.f};
.LBB0_3009:
	s_ashr_i32 s53, s52, 31
	s_lshl_b64 s[54:55], s[52:53], 19
	s_add_u32 s54, s37, s54
	s_addc_u32 s55, s39, s55
	s_and_b64 s[56:57], s[6:7], exec
	s_cselect_b32 s9, s55, s15
	s_cselect_b32 s11, s54, s14
	s_ashr_i32 s51, s50, 31
	s_lshl_b64 s[56:57], s[50:51], 19
	s_add_u32 s56, s41, s56
	s_addc_u32 s57, s43, s57
	s_and_b64 s[58:59], s[6:7], exec
	s_cselect_b32 s51, s57, s13
	s_cselect_b32 s53, s56, s12
	s_add_u32 s60, s12, 0x100
	s_addc_u32 s61, s13, 0
	s_add_u32 s12, s14, 0x40080
	v_mov_b32_e32 v0, 0
	s_addc_u32 s13, s15, 0
	s_mov_b32 s79, -2
	v_mov_b64_e32 v[2:3], 0
	v_mov_b64_e32 v[4:5], 0
	v_mov_b64_e32 v[6:7], 0
	v_mov_b64_e32 v[8:9], 0
	v_mov_b64_e32 v[10:11], 0
	v_mov_b64_e32 v[12:13], 0
	v_mov_b64_e32 v[14:15], 0
	v_mov_b64_e32 v[16:17], 0
	v_mov_b64_e32 v[18:19], 0
	v_mov_b64_e32 v[20:21], 0
	v_mov_b64_e32 v[22:23], 0
	v_mov_b64_e32 v[24:25], 0
	v_mov_b64_e32 v[26:27], 0
	v_mov_b64_e32 v[28:29], 0
	v_mov_b64_e32 v[30:31], 0
	v_mov_b64_e32 v[32:33], 0
	v_mov_b64_e32 v[34:35], 0
	v_mov_b64_e32 v[36:37], 0
	v_mov_b64_e32 v[38:39], 0
	v_mov_b64_e32 v[40:41], 0
	v_mov_b64_e32 v[42:43], 0
	v_mov_b64_e32 v[44:45], 0
	v_mov_b64_e32 v[46:47], 0
	v_mov_b64_e32 v[48:49], 0
	v_mov_b64_e32 v[50:51], 0
	v_mov_b64_e32 v[52:53], 0
	v_mov_b64_e32 v[54:55], 0
	v_mov_b64_e32 v[72:73], 0
	v_mov_b64_e32 v[74:75], 0
	v_mov_b64_e32 v[76:77], 0
	v_mov_b64_e32 v[78:79], 0
	v_mov_b64_e32 v[80:81], 0
	v_mov_b64_e32 v[82:83], 0
	v_mov_b64_e32 v[84:85], 0
	v_mov_b64_e32 v[86:87], 0
	v_mov_b64_e32 v[88:89], 0
	v_mov_b64_e32 v[90:91], 0
	v_mov_b64_e32 v[92:93], 0
	v_mov_b64_e32 v[94:95], 0
	v_mov_b64_e32 v[96:97], 0
	v_mov_b64_e32 v[98:99], 0
	v_mov_b64_e32 v[116:117], 0
	v_mov_b64_e32 v[118:119], 0
	v_mov_b64_e32 v[120:121], 0
	v_mov_b64_e32 v[122:123], 0
	v_mov_b64_e32 v[124:125], 0
	v_mov_b64_e32 v[126:127], 0
	v_mov_b64_e32 v[128:129], 0
	v_mov_b64_e32 v[130:131], 0
	v_mov_b64_e32 v[132:133], 0
	v_mov_b64_e32 v[134:135], 0
	v_mov_b64_e32 v[136:137], 0
	v_mov_b64_e32 v[138:139], 0
	v_mov_b64_e32 v[140:141], 0
	v_mov_b64_e32 v[142:143], 0
	v_mov_b64_e32 v[144:145], 0
	v_mov_b64_e32 v[146:147], 0
	v_mov_b64_e32 v[148:149], 0
	v_mov_b64_e32 v[150:151], 0
	v_mov_b64_e32 v[152:153], 0
	v_mov_b64_e32 v[154:155], 0
	v_mov_b64_e32 v[156:157], 0
	v_mov_b64_e32 v[158:159], 0
	v_mov_b32_e32 v1, v0

; template <class Epi, class Sched, bool ALIGN_EPI = false, bool SP2 = false>
; __device__ __forceinline__ void gemm_phase(PG8_LAS unsigned char* lds, const Gemm g, const Sched& S, const Epi& E, const int wave_s) {
;     ...
; #pragma unroll
;         for (int a = 0; a < 2; ++a)
; #pragma unroll
;             for (int b = 0; b < 2; ++b)
; #pragma unroll
;                 for (int m = 0; m < 4; ++m)
; #pragma unroll
;                     for (int n = 0; n < 2; ++n) acc[a][b][m][n] = (f32x4){0.f, 0.f, 0.f, 0.f};
;         cur = nxt; cA = nA; cB = nB; ++ui;
.LBB0_3119:
	s_add_u32 s59, s26, 0x100
	v_mov_b32_e32 v0, 0
	s_addc_u32 s60, s27, 0
	s_mov_b32 s61, -2
	v_mov_b64_e32 v[2:3], 0
	v_mov_b64_e32 v[4:5], 0
	v_mov_b64_e32 v[6:7], 0
	v_mov_b64_e32 v[8:9], 0
	v_mov_b64_e32 v[10:11], 0
	v_mov_b64_e32 v[12:13], 0
	v_mov_b64_e32 v[14:15], 0
	v_mov_b64_e32 v[16:17], 0
	v_mov_b64_e32 v[18:19], 0
	v_mov_b64_e32 v[20:21], 0
	v_mov_b64_e32 v[22:23], 0
	v_mov_b64_e32 v[24:25], 0
	v_mov_b64_e32 v[26:27], 0
	v_mov_b64_e32 v[28:29], 0
	v_mov_b64_e32 v[30:31], 0
	v_mov_b64_e32 v[32:33], 0
	v_mov_b64_e32 v[34:35], 0
	v_mov_b64_e32 v[36:37], 0
	v_mov_b64_e32 v[38:39], 0
	v_mov_b64_e32 v[40:41], 0
	v_mov_b64_e32 v[42:43], 0
	v_mov_b64_e32 v[44:45], 0
	v_mov_b64_e32 v[46:47], 0
	v_mov_b64_e32 v[48:49], 0
	v_mov_b64_e32 v[50:51], 0
	v_mov_b64_e32 v[52:53], 0
	v_mov_b64_e32 v[54:55], 0
	v_mov_b64_e32 v[56:57], 0
	v_mov_b64_e32 v[58:59], 0
	v_mov_b64_e32 v[60:61], 0
	v_mov_b64_e32 v[62:63], 0
	v_mov_b64_e32 v[64:65], 0
	v_mov_b64_e32 v[66:67], 0
	v_mov_b64_e32 v[68:69], 0
	v_mov_b64_e32 v[70:71], 0
	v_mov_b64_e32 v[72:73], 0
	v_mov_b64_e32 v[74:75], 0
	v_mov_b64_e32 v[76:77], 0
	v_mov_b64_e32 v[78:79], 0
	v_mov_b64_e32 v[80:81], 0
	v_mov_b64_e32 v[82:83], 0
	v_mov_b64_e32 v[84:85], 0
	v_mov_b64_e32 v[86:87], 0
	v_mov_b64_e32 v[88:89], 0
	v_mov_b64_e32 v[90:91], 0
	v_mov_b64_e32 v[92:93], 0
	v_mov_b64_e32 v[94:95], 0
	v_mov_b64_e32 v[96:97], 0
	v_mov_b64_e32 v[98:99], 0
	v_mov_b64_e32 v[100:101], 0
	v_mov_b64_e32 v[102:103], 0
	v_mov_b64_e32 v[104:105], 0
	v_mov_b64_e32 v[106:107], 0
	v_mov_b64_e32 v[108:109], 0
	v_mov_b64_e32 v[110:111], 0
	v_mov_b64_e32 v[112:113], 0
	v_mov_b64_e32 v[114:115], 0
	v_mov_b64_e32 v[116:117], 0
	v_mov_b64_e32 v[118:119], 0
	v_mov_b64_e32 v[120:121], 0
	v_mov_b64_e32 v[122:123], 0
	v_mov_b64_e32 v[124:125], 0
	v_mov_b64_e32 v[126:127], 0
	v_mov_b32_e32 v1, v0
